# NSA compressed pass B loop hand-scheduled (K-frag prefetch, fragment reads grouped, importance hook via DPP adds, visibility test only on the last two tiles); pass A: visibility test on the last two t
# speedup vs baseline: 1.0091x; 1.0003x over previous
.LBB0_835:
	s_add_i32 s2, s41, 1
	s_cmp_ge_i32 s2, s38
	s_cbranch_scc1 .Lcmpa_masked
	s_and_b32 s42, s41, 1
	s_xor_b32 s2, s42, 1
	s_mulk_i32 s2, 0x2400
	s_mulk_i32 s42, 0x2400
	v_add_u32_e32 v44, s42, v129
	v_add_u32_e32 v45, s2, v127
	ds_read_b128 v[202:205], v44 offset:4608
	ds_read_b128 v[206:209], v44 offset:4672
	ds_read_b128 v[210:213], v44 offset:6912
	ds_read_b128 v[218:221], v44 offset:6976
	v_add_u32_e32 v44, s2, v129
	s_waitcnt lgkmcnt(5)
	v_mfma_f32_16x16x32_bf16 v[64:67], v[186:189], v[0:3], 0
	v_mfma_f32_16x16x32_bf16 v[68:71], v[186:189], v[8:11], 0
	v_mfma_f32_16x16x32_bf16 v[222:225], v[194:197], v[0:3], 0
	v_mfma_f32_16x16x32_bf16 v[226:229], v[194:197], v[8:11], 0
	s_waitcnt vmcnt(1)
	ds_write_b128 v45, v[20:23]
	s_waitcnt lgkmcnt(5)
	v_mfma_f32_16x16x32_bf16 v[64:67], v[190:193], v[4:7], v[64:67]
	v_mfma_f32_16x16x32_bf16 v[68:71], v[190:193], v[12:15], v[68:71]
	v_mfma_f32_16x16x32_bf16 v[222:225], v[198:201], v[4:7], v[222:225]
	v_mfma_f32_16x16x32_bf16 v[226:229], v[198:201], v[12:15], v[226:229]
	s_waitcnt vmcnt(0)
	ds_write_b128 v45, v[24:27] offset:4608
	s_add_i32 s2, s41, 2
	s_min_i32 s43, s2, s38
	s_lshl_b32 s44, s43, 13
	v_lshl_add_u64 v[20:21], v[154:155], 0, s[44:45]
	v_add_co_u32_e32 v24, vcc, s47, v20
	s_nop 0
	v_addc_co_u32_e32 v25, vcc, 0, v21, vcc
	global_load_dwordx4 v[20:23], v[20:21], off
	global_load_dwordx4 v[24:27], v[24:25], off
	s_waitcnt lgkmcnt(3)
	v_mfma_f32_16x16x32_bf16 v[230:233], v[202:205], v[0:3], 0
	v_mfma_f32_16x16x32_bf16 v[234:237], v[202:205], v[8:11], 0
	v_mfma_f32_16x16x32_bf16 v[238:241], v[210:213], v[0:3], 0
	v_mfma_f32_16x16x32_bf16 v[242:245], v[210:213], v[8:11], 0
	s_waitcnt lgkmcnt(2)
	v_mfma_f32_16x16x32_bf16 v[230:233], v[206:209], v[4:7], v[230:233]
	v_mfma_f32_16x16x32_bf16 v[234:237], v[206:209], v[12:15], v[234:237]
	v_mfma_f32_16x16x32_bf16 v[238:241], v[218:221], v[4:7], v[238:241]
	v_mfma_f32_16x16x32_bf16 v[242:245], v[218:221], v[12:15], v[242:245]
	s_setprio 0
	s_add_i32 s41, s41, 1
	s_add_i32 s39, s39, 64
	v_exp_f32_e32 v64, v64
	v_exp_f32_e32 v68, v68
	v_exp_f32_e32 v65, v65
	v_exp_f32_e32 v69, v69
	v_exp_f32_e32 v66, v66
	v_exp_f32_e32 v70, v70
	v_exp_f32_e32 v67, v67
	v_exp_f32_e32 v71, v71
	v_pk_add_f32 v[54:55], v[54:55], v[64:65]
	v_pk_add_f32 v[56:57], v[56:57], v[68:69]
	v_pk_add_f32 v[54:55], v[54:55], v[66:67]
	v_pk_add_f32 v[56:57], v[56:57], v[70:71]
	v_exp_f32_e32 v222, v222
	v_exp_f32_e32 v226, v226
	v_exp_f32_e32 v223, v223
	v_exp_f32_e32 v227, v227
	v_exp_f32_e32 v224, v224
	v_exp_f32_e32 v228, v228
	v_exp_f32_e32 v225, v225
	v_exp_f32_e32 v229, v229
	v_pk_add_f32 v[54:55], v[54:55], v[222:223]
	v_pk_add_f32 v[56:57], v[56:57], v[226:227]
	v_pk_add_f32 v[54:55], v[54:55], v[224:225]
	v_pk_add_f32 v[56:57], v[56:57], v[228:229]
	s_waitcnt lgkmcnt(0)
	s_barrier
	ds_read_b128 v[186:189], v44 offset:0
	ds_read_b128 v[190:193], v44 offset:64
	ds_read_b128 v[194:197], v44 offset:2304
	ds_read_b128 v[198:201], v44 offset:2368
	v_exp_f32_e32 v230, v230
	v_exp_f32_e32 v234, v234
	v_exp_f32_e32 v231, v231
	v_exp_f32_e32 v235, v235
	v_exp_f32_e32 v232, v232
	v_exp_f32_e32 v236, v236
	v_exp_f32_e32 v233, v233
	v_exp_f32_e32 v237, v237
	v_pk_add_f32 v[54:55], v[54:55], v[230:231]
	v_pk_add_f32 v[56:57], v[56:57], v[234:235]
	v_pk_add_f32 v[54:55], v[54:55], v[232:233]
	v_pk_add_f32 v[56:57], v[56:57], v[236:237]
	v_exp_f32_e32 v238, v238
	v_exp_f32_e32 v242, v242
	v_exp_f32_e32 v239, v239
	v_exp_f32_e32 v243, v243
	v_exp_f32_e32 v240, v240
	v_exp_f32_e32 v244, v244
	v_exp_f32_e32 v241, v241
	v_exp_f32_e32 v245, v245
	v_pk_add_f32 v[54:55], v[54:55], v[238:239]
	v_pk_add_f32 v[56:57], v[56:57], v[242:243]
	v_pk_add_f32 v[54:55], v[54:55], v[240:241]
	v_pk_add_f32 v[56:57], v[56:57], v[244:245]
	s_setprio 2
	s_cmp_lg_u32 s40, s41
	s_cbranch_scc1 .LBB0_835
	s_branch .Lcmpa_done

.Lcmpa_done:
	s_waitcnt lgkmcnt(0)
	s_setprio 1
	v_add_f32_e32 v61, v54, v55
	v_add_f32_e32 v60, v56, v57
	global_load_dwordx4 v[62:65], v[154:155], off
	global_load_dwordx4 v[66:69], v[156:157], off
	global_load_dwordx4 v[70:73], v[40:41], off
	global_load_dwordx4 v[188:191], v[42:43], off
	global_load_dwordx4 v[16:19], v[32:33], off
	global_load_dwordx4 v[20:23], v[34:35], off
	global_load_dwordx4 v[24:27], v[36:37], off
	global_load_dwordx4 v[28:31], v[38:39], off
	v_and_b32_e32 v33, 64, v121
	v_xor_b32_e32 v59, 16, v121
	v_add_u32_e32 v187, 64, v33
	v_cmp_lt_i32_e32 vcc, v59, v187
	v_xor_b32_e32 v162, 32, v121
	v_xor_b32_e32 v163, 1, v121
	v_cndmask_b32_e32 v59, v121, v59, vcc
	v_lshlrev_b32_e32 v182, 2, v59
	ds_bpermute_b32 v75, v182, v61
	ds_bpermute_b32 v74, v182, v60
	v_cmp_lt_i32_e32 vcc, v162, v187
	v_xor_b32_e32 v186, 2, v121
	s_mul_i32 s42, s33, 0x1020
	v_cndmask_b32_e32 v162, v121, v162, vcc
	v_lshlrev_b32_e32 v183, 2, v162
	s_waitcnt lgkmcnt(0)
	v_pk_add_f32 v[60:61], v[60:61], v[74:75]
	ds_bpermute_b32 v75, v183, v61
	ds_bpermute_b32 v74, v183, v60
	v_cmp_lt_i32_e32 vcc, v163, v187
	v_mov_b32_e32 v32, 0
	s_movk_i32 s47, 0x4000
	v_cndmask_b32_e32 v162, v121, v163, vcc
	s_waitcnt lgkmcnt(0)
	v_pk_add_f32 v[60:61], v[60:61], v[74:75]
	v_cmp_lt_i32_e32 vcc, v186, v187
	v_log_f32_e32 v74, v61
	v_log_f32_e32 v75, v60
	v_cndmask_b32_e32 v163, v121, v186, vcc
	v_cmp_lt_f32_e32 vcc, 0, v61
	s_movk_i32 s43, 0x1000
	s_mov_b32 s33, 2
	v_cndmask_b32_e64 v186, 0, -v74, vcc
	v_cmp_lt_f32_e32 vcc, 0, v60
	s_not_b32 s39, s38
	v_add_u32_e32 v159, s42, v174
	v_add_u32_e32 v160, s42, v175
	v_add_u32_e32 v161, s42, v176
	v_mov_b32_e32 v33, v32
	v_mov_b32_e32 v34, v32
	v_mov_b32_e32 v35, v32
	v_mov_b32_e32 v36, v32
	v_mov_b32_e32 v37, v32
	v_mov_b32_e32 v38, v32
	v_mov_b32_e32 v39, v32
	v_mov_b32_e32 v40, v32
	v_mov_b32_e32 v41, v32
	v_mov_b32_e32 v42, v32
	v_mov_b32_e32 v43, v32
	v_mov_b32_e32 v44, v32
	v_mov_b32_e32 v45, v32
	v_mov_b32_e32 v46, v32
	v_mov_b32_e32 v47, v32
	v_mov_b32_e32 v48, v32
	v_mov_b32_e32 v49, v32
	v_mov_b32_e32 v50, v32
	v_mov_b32_e32 v51, v32
	v_mov_b32_e32 v52, v32
	v_mov_b32_e32 v53, v32
	v_mov_b32_e32 v54, v32
	v_mov_b32_e32 v55, v32
	v_mov_b32_e32 v56, v32
	v_mov_b32_e32 v57, v32
	v_mov_b32_e32 v58, v32
	v_mov_b32_e32 v59, v32
	v_lshlrev_b32_e32 v162, 2, v162
	v_lshlrev_b32_e32 v163, 2, v163
	v_cndmask_b32_e64 v187, 0, -v75, vcc
	v_mov_b32_e32 v60, v32
	v_mov_b32_e32 v61, v32
	v_readlane_b32 s50, v250, 56
	v_readlane_b32 s51, v250, 57
	s_waitcnt vmcnt(7)
	ds_write_b128 v127, v[62:65]
	s_waitcnt vmcnt(6)
	ds_write_b128 v127, v[66:69] offset:18432
	s_waitcnt vmcnt(5)
	ds_write_b128 v127, v[70:73] offset:4608
	s_waitcnt vmcnt(4)
	ds_write_b128 v127, v[188:191] offset:23040
	v_mov_b32_e32 v62, v32
	v_mov_b32_e32 v63, v32
	s_waitcnt lgkmcnt(0)
	s_barrier
	ds_read_b128 v[190:193], v129 offset:0
	ds_read_b128 v[194:197], v129 offset:64
	ds_read_b128 v[198:201], v129 offset:2304
	ds_read_b128 v[202:205], v129 offset:2368
.LBB0_838:
	s_add_i32 s2, s33, -1
	s_cmp_ge_i32 s2, s38
	s_cbranch_scc1 .Lcmpb_masked
	s_add_i32 s2, s33, -2
	s_and_b32 s40, s2, 1
	s_xor_b32 s2, s40, 1
	s_mulk_i32 s2, 0x2400
	s_mulk_i32 s40, 0x2400
	v_add_u32_e32 v188, s40, v129
	v_add_u32_e32 v189, s2, v127
	v_add_u32_e32 v217, s40, v131
	ds_read_b128 v[206:209], v188 offset:4608
	ds_read_b128 v[210:213], v188 offset:4672
	ds_read_b128 v[218:221], v188 offset:6912
	ds_read_b128 v[222:225], v188 offset:6976
	v_add_u32_e32 v188, s2, v129
	s_waitcnt lgkmcnt(5)
	v_mfma_f32_16x16x32_bf16 v[64:67], v[190:193], v[0:3], 0
	v_mfma_f32_16x16x32_bf16 v[68:71], v[190:193], v[8:11], 0
	v_mfma_f32_16x16x32_bf16 v[72:75], v[198:201], v[0:3], 0
	v_mfma_f32_16x16x32_bf16 v[226:229], v[198:201], v[8:11], 0
	s_waitcnt vmcnt(2)
	ds_write_b128 v189, v[20:23]
	ds_write_b128 v189, v[16:19] offset:18432
	s_waitcnt lgkmcnt(6)
	v_mfma_f32_16x16x32_bf16 v[64:67], v[194:197], v[4:7], v[64:67]
	v_mfma_f32_16x16x32_bf16 v[68:71], v[194:197], v[12:15], v[68:71]
	v_mfma_f32_16x16x32_bf16 v[72:75], v[202:205], v[4:7], v[72:75]
	v_mfma_f32_16x16x32_bf16 v[226:229], v[202:205], v[12:15], v[226:229]
	s_waitcnt vmcnt(0)
	ds_write_b128 v189, v[24:27] offset:4608
	ds_write_b128 v189, v[28:31] offset:23040
	s_min_i32 s41, s33, s38
	s_lshl_b32 s44, s41, 13
	s_lshl_b32 s2, s41, 7
	s_mov_b32 s3, s45
	v_lshl_add_u64 v[20:21], v[154:155], 0, s[44:45]
	v_lshl_add_u64 v[16:17], v[156:157], 0, s[2:3]
	v_add_co_u32_e32 v24, vcc, s43, v20
	s_nop 0
	v_addc_co_u32_e32 v25, vcc, 0, v21, vcc
	v_add_co_u32_e32 v28, vcc, s47, v16
	s_nop 0
	v_addc_co_u32_e32 v29, vcc, 0, v17, vcc
	global_load_dwordx4 v[20:23], v[20:21], off
	global_load_dwordx4 v[16:19], v[16:17], off
	global_load_dwordx4 v[24:27], v[24:25], off
	global_load_dwordx4 v[28:31], v[28:29], off
	ds_read_b64 v[190:191], v217 offset:18432
	ds_read_b64 v[192:193], v217 offset:18464
	ds_read_b64 v[194:195], v217 offset:20736
	ds_read_b64 v[196:197], v217 offset:20768
	ds_read_b64 v[198:199], v217 offset:23040
	ds_read_b64 v[200:201], v217 offset:23072
	ds_read_b64 v[202:203], v217 offset:25344
	s_waitcnt lgkmcnt(13)
	ds_read_b64 v[204:205], v217 offset:25376
	s_waitcnt lgkmcnt(13)
	v_mfma_f32_16x16x32_bf16 v[230:233], v[206:209], v[0:3], 0
	v_mfma_f32_16x16x32_bf16 v[234:237], v[206:209], v[8:11], 0
	v_mfma_f32_16x16x32_bf16 v[238:241], v[218:221], v[0:3], 0
	v_mfma_f32_16x16x32_bf16 v[242:245], v[218:221], v[8:11], 0
	s_waitcnt lgkmcnt(12)
	v_mfma_f32_16x16x32_bf16 v[230:233], v[210:213], v[4:7], v[230:233]
	v_mfma_f32_16x16x32_bf16 v[234:237], v[210:213], v[12:15], v[234:237]
	v_mfma_f32_16x16x32_bf16 v[238:241], v[222:225], v[4:7], v[238:241]
	v_mfma_f32_16x16x32_bf16 v[242:245], v[222:225], v[12:15], v[242:245]
	ds_read_b64 v[206:207], v217 offset:18496
	ds_read_b64 v[208:209], v217 offset:18528
	ds_read_b64 v[210:211], v217 offset:20800
	s_waitcnt lgkmcnt(13)
	ds_read_b64 v[212:213], v217 offset:20832
	ds_read_b64 v[218:219], v217 offset:23104
	s_waitcnt lgkmcnt(13)
	ds_read_b64 v[220:221], v217 offset:23136
	ds_read_b64 v[222:223], v217 offset:25408
	s_waitcnt lgkmcnt(13)
	ds_read_b64 v[224:225], v217 offset:25440
	s_setprio 0
	v_add_f32_e32 v64, v186, v64
	v_add_f32_e32 v68, v187, v68
	v_add_f32_e32 v65, v186, v65
	v_add_f32_e32 v69, v187, v69
	v_add_f32_e32 v66, v186, v66
	v_add_f32_e32 v70, v187, v70
	v_add_f32_e32 v67, v186, v67
	v_add_f32_e32 v71, v187, v71
	v_exp_f32_e32 v64, v64
	v_exp_f32_e32 v68, v68
	v_exp_f32_e32 v65, v65
	v_exp_f32_e32 v69, v69
	v_exp_f32_e32 v66, v66
	v_exp_f32_e32 v70, v70
	v_exp_f32_e32 v67, v67
	v_exp_f32_e32 v71, v71
	v_add_f32_e32 v162, v64, v65
	v_add_f32_e32 v163, v68, v69
	v_add_f32_e32 v162, v66, v162
	v_add_f32_e32 v163, v70, v163
	v_mul_f32_e32 v246, 0.5, v67
	v_mul_f32_e32 v247, 0.5, v71
	v_fmac_f32_e32 v162, 0.5, v67
	v_fmac_f32_e32 v163, 0.5, v71
	s_nop 1
	v_add_f32_dpp v162, v162, v162 quad_perm:[1,0,3,2] row_mask:0xf bank_mask:0xf
	v_add_f32_dpp v163, v163, v163 quad_perm:[1,0,3,2] row_mask:0xf bank_mask:0xf
	v_add_f32_dpp v246, v246, v246 quad_perm:[1,0,3,2] row_mask:0xf bank_mask:0xf
	v_add_f32_dpp v247, v247, v247 quad_perm:[1,0,3,2] row_mask:0xf bank_mask:0xf
	v_add_f32_dpp v162, v162, v162 quad_perm:[2,3,0,1] row_mask:0xf bank_mask:0xf
	v_add_f32_dpp v163, v163, v163 quad_perm:[2,3,0,1] row_mask:0xf bank_mask:0xf
	v_add_f32_dpp v246, v246, v246 quad_perm:[2,3,0,1] row_mask:0xf bank_mask:0xf
	v_add_f32_dpp v247, v247, v247 quad_perm:[2,3,0,1] row_mask:0xf bank_mask:0xf
	s_and_saveexec_b64 s[40:41], s[4:5]
	ds_write_b32 v161, v162
	s_waitcnt lgkmcnt(13)
	ds_write_b32 v160, v246
	ds_write_b32 v159, v163
	s_waitcnt lgkmcnt(13)
	ds_write_b32 v160, v247 offset:1040
	s_mov_b64 exec, s[40:41]
	v_add_f32_e32 v72, v186, v72
	v_add_f32_e32 v226, v187, v226
	v_add_f32_e32 v73, v186, v73
	v_add_f32_e32 v227, v187, v227
	v_add_f32_e32 v74, v186, v74
	v_add_f32_e32 v228, v187, v228
	v_add_f32_e32 v75, v186, v75
	v_add_f32_e32 v229, v187, v229
	v_exp_f32_e32 v72, v72
	v_exp_f32_e32 v226, v226
	v_exp_f32_e32 v73, v73
	v_exp_f32_e32 v227, v227
	v_exp_f32_e32 v74, v74
	v_exp_f32_e32 v228, v228
	v_exp_f32_e32 v75, v75
	v_exp_f32_e32 v229, v229
	v_add_f32_e32 v162, v72, v73
	v_add_f32_e32 v163, v226, v227
	v_add_f32_e32 v162, v74, v162
	v_add_f32_e32 v163, v228, v163
	v_mul_f32_e32 v246, 0.5, v75
	v_mul_f32_e32 v247, 0.5, v229
	v_fmac_f32_e32 v162, 0.5, v75
	v_fmac_f32_e32 v163, 0.5, v229
	s_nop 1
	v_add_f32_dpp v162, v162, v162 quad_perm:[1,0,3,2] row_mask:0xf bank_mask:0xf
	v_add_f32_dpp v163, v163, v163 quad_perm:[1,0,3,2] row_mask:0xf bank_mask:0xf
	v_add_f32_dpp v246, v246, v246 quad_perm:[1,0,3,2] row_mask:0xf bank_mask:0xf
	v_add_f32_dpp v247, v247, v247 quad_perm:[1,0,3,2] row_mask:0xf bank_mask:0xf
	v_add_f32_dpp v162, v162, v162 quad_perm:[2,3,0,1] row_mask:0xf bank_mask:0xf
	v_add_f32_dpp v163, v163, v163 quad_perm:[2,3,0,1] row_mask:0xf bank_mask:0xf
	v_add_f32_dpp v246, v246, v246 quad_perm:[2,3,0,1] row_mask:0xf bank_mask:0xf
	v_add_f32_dpp v247, v247, v247 quad_perm:[2,3,0,1] row_mask:0xf bank_mask:0xf
	s_and_saveexec_b64 s[40:41], s[4:5]
	ds_write_b32 v161, v162 offset:16
	s_waitcnt lgkmcnt(13)
	ds_write_b32 v160, v246 offset:16
	ds_write_b32 v159, v163 offset:16
	s_waitcnt lgkmcnt(13)
	ds_write_b32 v160, v247 offset:1056
	s_mov_b64 exec, s[40:41]
	v_cvt_pk_bf16_f32 v64, v64, v65
	v_cvt_pk_bf16_f32 v65, v66, v67
	v_cvt_pk_bf16_f32 v66, v72, v73
	v_cvt_pk_bf16_f32 v67, v74, v75
	v_cvt_pk_bf16_f32 v68, v68, v69
	v_cvt_pk_bf16_f32 v69, v70, v71
	v_cvt_pk_bf16_f32 v70, v226, v227
	v_cvt_pk_bf16_f32 v71, v228, v229
	s_waitcnt lgkmcnt(0)
	s_barrier
	v_add_f32_e32 v230, v186, v230
	v_add_f32_e32 v234, v187, v234
	v_add_f32_e32 v231, v186, v231
	v_add_f32_e32 v235, v187, v235
	v_add_f32_e32 v232, v186, v232
	v_add_f32_e32 v236, v187, v236
	v_add_f32_e32 v233, v186, v233
	v_add_f32_e32 v237, v187, v237
	v_exp_f32_e32 v230, v230
	v_mfma_f32_16x16x32_bf16 v[60:63], v[190:193], v[64:67], v[60:63]
	v_exp_f32_e32 v234, v234
	v_exp_f32_e32 v231, v231
	v_exp_f32_e32 v235, v235
	v_exp_f32_e32 v232, v232
	v_exp_f32_e32 v236, v236
	v_exp_f32_e32 v233, v233
	v_exp_f32_e32 v237, v237
	v_add_f32_e32 v162, v230, v231
	v_add_f32_e32 v163, v234, v235
	v_mfma_f32_16x16x32_bf16 v[44:47], v[190:193], v[68:71], v[44:47]
	v_add_f32_e32 v162, v232, v162
	v_add_f32_e32 v163, v236, v163
	v_mul_f32_e32 v246, 0.5, v233
	v_mul_f32_e32 v247, 0.5, v237
	v_fmac_f32_e32 v162, 0.5, v233
	v_fmac_f32_e32 v163, 0.5, v237
	s_nop 1
	v_add_f32_dpp v162, v162, v162 quad_perm:[1,0,3,2] row_mask:0xf bank_mask:0xf
	v_add_f32_dpp v163, v163, v163 quad_perm:[1,0,3,2] row_mask:0xf bank_mask:0xf
	v_mfma_f32_16x16x32_bf16 v[56:59], v[194:197], v[64:67], v[56:59]
	v_add_f32_dpp v246, v246, v246 quad_perm:[1,0,3,2] row_mask:0xf bank_mask:0xf
	v_add_f32_dpp v247, v247, v247 quad_perm:[1,0,3,2] row_mask:0xf bank_mask:0xf
	v_add_f32_dpp v162, v162, v162 quad_perm:[2,3,0,1] row_mask:0xf bank_mask:0xf
	v_add_f32_dpp v163, v163, v163 quad_perm:[2,3,0,1] row_mask:0xf bank_mask:0xf
	v_add_f32_dpp v246, v246, v246 quad_perm:[2,3,0,1] row_mask:0xf bank_mask:0xf
	v_add_f32_dpp v247, v247, v247 quad_perm:[2,3,0,1] row_mask:0xf bank_mask:0xf
	s_and_saveexec_b64 s[40:41], s[4:5]
	ds_write_b32 v161, v162 offset:32
	ds_write_b32 v160, v246 offset:32
	ds_write_b32 v159, v163 offset:32
	ds_write_b32 v160, v247 offset:1072
	s_mov_b64 exec, s[40:41]
	v_add_f32_e32 v238, v186, v238
	v_add_f32_e32 v242, v187, v242
	v_mfma_f32_16x16x32_bf16 v[40:43], v[194:197], v[68:71], v[40:43]
	v_add_f32_e32 v239, v186, v239
	v_add_f32_e32 v243, v187, v243
	v_add_f32_e32 v240, v186, v240
	v_add_f32_e32 v244, v187, v244
	v_add_f32_e32 v241, v186, v241
	v_add_f32_e32 v245, v187, v245
	v_exp_f32_e32 v238, v238
	v_exp_f32_e32 v242, v242
	v_exp_f32_e32 v239, v239
	v_mfma_f32_16x16x32_bf16 v[52:55], v[198:201], v[64:67], v[52:55]
	v_exp_f32_e32 v243, v243
	v_exp_f32_e32 v240, v240
	v_exp_f32_e32 v244, v244
	v_exp_f32_e32 v241, v241
	v_exp_f32_e32 v245, v245
	v_add_f32_e32 v162, v238, v239
	v_add_f32_e32 v163, v242, v243
	v_add_f32_e32 v162, v240, v162
	v_add_f32_e32 v163, v244, v163
	v_mfma_f32_16x16x32_bf16 v[36:39], v[198:201], v[68:71], v[36:39]
	v_mul_f32_e32 v246, 0.5, v241
	v_mul_f32_e32 v247, 0.5, v245
	v_fmac_f32_e32 v162, 0.5, v241
	v_fmac_f32_e32 v163, 0.5, v245
	s_nop 1
	v_add_f32_dpp v162, v162, v162 quad_perm:[1,0,3,2] row_mask:0xf bank_mask:0xf
	v_add_f32_dpp v163, v163, v163 quad_perm:[1,0,3,2] row_mask:0xf bank_mask:0xf
	v_add_f32_dpp v246, v246, v246 quad_perm:[1,0,3,2] row_mask:0xf bank_mask:0xf
	v_add_f32_dpp v247, v247, v247 quad_perm:[1,0,3,2] row_mask:0xf bank_mask:0xf
	v_mfma_f32_16x16x32_bf16 v[48:51], v[202:205], v[64:67], v[48:51]
	v_add_f32_dpp v162, v162, v162 quad_perm:[2,3,0,1] row_mask:0xf bank_mask:0xf
	v_add_f32_dpp v163, v163, v163 quad_perm:[2,3,0,1] row_mask:0xf bank_mask:0xf
	v_add_f32_dpp v246, v246, v246 quad_perm:[2,3,0,1] row_mask:0xf bank_mask:0xf
	v_add_f32_dpp v247, v247, v247 quad_perm:[2,3,0,1] row_mask:0xf bank_mask:0xf
	s_and_saveexec_b64 s[40:41], s[4:5]
	ds_write_b32 v161, v162 offset:48
	ds_write_b32 v160, v246 offset:48
	ds_write_b32 v159, v163 offset:48
	ds_write_b32 v160, v247 offset:1088
	s_mov_b64 exec, s[40:41]
	v_cvt_pk_bf16_f32 v230, v230, v231
	v_cvt_pk_bf16_f32 v231, v232, v233
	v_cvt_pk_bf16_f32 v232, v238, v239
	v_cvt_pk_bf16_f32 v233, v240, v241
	v_mfma_f32_16x16x32_bf16 v[32:35], v[202:205], v[68:71], v[32:35]
	v_cvt_pk_bf16_f32 v234, v234, v235
	v_cvt_pk_bf16_f32 v235, v236, v237
	v_cvt_pk_bf16_f32 v236, v242, v243
	v_cvt_pk_bf16_f32 v237, v244, v245
	v_add_u32_e32 v159, 64, v159
	v_add_u32_e32 v160, 64, v160
	v_add_u32_e32 v161, 64, v161
	v_subrev_u32_e32 v158, 64, v158
	v_subrev_u32_e32 v113, 64, v113
	s_add_i32 s33, s33, 1
	s_add_i32 s2, s39, s33
	s_waitcnt lgkmcnt(0)
	ds_read_b128 v[190:193], v188 offset:0
	ds_read_b128 v[194:197], v188 offset:64
	ds_read_b128 v[198:201], v188 offset:2304
	ds_read_b128 v[202:205], v188 offset:2368
	s_setprio 2
	v_mfma_f32_16x16x32_bf16 v[60:63], v[206:209], v[230:233], v[60:63]
	v_mfma_f32_16x16x32_bf16 v[44:47], v[206:209], v[234:237], v[44:47]
	v_mfma_f32_16x16x32_bf16 v[56:59], v[210:213], v[230:233], v[56:59]
	v_mfma_f32_16x16x32_bf16 v[40:43], v[210:213], v[234:237], v[40:43]
	v_mfma_f32_16x16x32_bf16 v[52:55], v[218:221], v[230:233], v[52:55]
	v_mfma_f32_16x16x32_bf16 v[36:39], v[218:221], v[234:237], v[36:39]
	v_mfma_f32_16x16x32_bf16 v[48:51], v[222:225], v[230:233], v[48:51]
	v_mfma_f32_16x16x32_bf16 v[32:35], v[222:225], v[234:237], v[32:35]
	s_cmp_lg_u32 s2, 2
	s_cbranch_scc1 .LBB0_838
	s_branch .Lcmpb_done
.Lcmpb_masked:
	s_add_i32 s2, s33, -2
	s_and_b32 s40, s2, 1
	s_xor_b32 s2, s40, 1
	s_mulk_i32 s2, 0x2400
	s_mulk_i32 s40, 0x2400
	v_add_u32_e32 v188, s40, v129
	v_add_u32_e32 v189, s2, v127
	v_add_u32_e32 v217, s40, v131
	ds_read_b128 v[206:209], v188 offset:4608
	ds_read_b128 v[210:213], v188 offset:4672
	ds_read_b128 v[218:221], v188 offset:6912
	ds_read_b128 v[222:225], v188 offset:6976
	v_add_u32_e32 v188, s2, v129
	s_waitcnt lgkmcnt(5)
	v_mfma_f32_16x16x32_bf16 v[64:67], v[190:193], v[0:3], 0
	v_mfma_f32_16x16x32_bf16 v[68:71], v[190:193], v[8:11], 0
	v_mfma_f32_16x16x32_bf16 v[72:75], v[198:201], v[0:3], 0
	v_mfma_f32_16x16x32_bf16 v[226:229], v[198:201], v[8:11], 0
	s_waitcnt vmcnt(2)
	ds_write_b128 v189, v[20:23]
	ds_write_b128 v189, v[16:19] offset:18432
	s_waitcnt lgkmcnt(6)
	v_mfma_f32_16x16x32_bf16 v[64:67], v[194:197], v[4:7], v[64:67]
	v_mfma_f32_16x16x32_bf16 v[68:71], v[194:197], v[12:15], v[68:71]
	v_mfma_f32_16x16x32_bf16 v[72:75], v[202:205], v[4:7], v[72:75]
	v_mfma_f32_16x16x32_bf16 v[226:229], v[202:205], v[12:15], v[226:229]
	s_waitcnt vmcnt(0)
	ds_write_b128 v189, v[24:27] offset:4608
	ds_write_b128 v189, v[28:31] offset:23040
	s_min_i32 s41, s33, s38
	s_lshl_b32 s44, s41, 13
	s_lshl_b32 s2, s41, 7
	s_mov_b32 s3, s45
	v_lshl_add_u64 v[20:21], v[154:155], 0, s[44:45]
	v_lshl_add_u64 v[16:17], v[156:157], 0, s[2:3]
	v_add_co_u32_e32 v24, vcc, s43, v20
	s_nop 0
	v_addc_co_u32_e32 v25, vcc, 0, v21, vcc
	v_add_co_u32_e32 v28, vcc, s47, v16
	s_nop 0
	v_addc_co_u32_e32 v29, vcc, 0, v17, vcc
	global_load_dwordx4 v[20:23], v[20:21], off
	global_load_dwordx4 v[16:19], v[16:17], off
	global_load_dwordx4 v[24:27], v[24:25], off
	global_load_dwordx4 v[28:31], v[28:29], off
	ds_read_b64 v[190:191], v217 offset:18432
	ds_read_b64 v[192:193], v217 offset:18464
	ds_read_b64 v[194:195], v217 offset:20736
	ds_read_b64 v[196:197], v217 offset:20768
	ds_read_b64 v[198:199], v217 offset:23040
	ds_read_b64 v[200:201], v217 offset:23072
	ds_read_b64 v[202:203], v217 offset:25344
	s_waitcnt lgkmcnt(13)
	ds_read_b64 v[204:205], v217 offset:25376
	s_waitcnt lgkmcnt(13)
	v_mfma_f32_16x16x32_bf16 v[230:233], v[206:209], v[0:3], 0
	v_mfma_f32_16x16x32_bf16 v[234:237], v[206:209], v[8:11], 0
	v_mfma_f32_16x16x32_bf16 v[238:241], v[218:221], v[0:3], 0
	v_mfma_f32_16x16x32_bf16 v[242:245], v[218:221], v[8:11], 0
	s_waitcnt lgkmcnt(12)
	v_mfma_f32_16x16x32_bf16 v[230:233], v[210:213], v[4:7], v[230:233]
	v_mfma_f32_16x16x32_bf16 v[234:237], v[210:213], v[12:15], v[234:237]
	v_mfma_f32_16x16x32_bf16 v[238:241], v[222:225], v[4:7], v[238:241]
	v_mfma_f32_16x16x32_bf16 v[242:245], v[222:225], v[12:15], v[242:245]
	ds_read_b64 v[206:207], v217 offset:18496
	ds_read_b64 v[208:209], v217 offset:18528
	ds_read_b64 v[210:211], v217 offset:20800
	s_waitcnt lgkmcnt(13)
	ds_read_b64 v[212:213], v217 offset:20832
	ds_read_b64 v[218:219], v217 offset:23104
	s_waitcnt lgkmcnt(13)
	ds_read_b64 v[220:221], v217 offset:23136
	ds_read_b64 v[222:223], v217 offset:25408
	s_waitcnt lgkmcnt(13)
	ds_read_b64 v[224:225], v217 offset:25440
	s_setprio 0
	v_add_f32_e32 v64, v186, v64
	v_add_f32_e32 v68, v187, v68
	v_add_f32_e32 v65, v186, v65
	v_add_f32_e32 v69, v187, v69
	v_add_f32_e32 v66, v186, v66
	v_add_f32_e32 v70, v187, v70
	v_add_f32_e32 v67, v186, v67
	v_add_f32_e32 v71, v187, v71
	v_exp_f32_e32 v64, v64
	v_exp_f32_e32 v68, v68
	v_exp_f32_e32 v65, v65
	v_exp_f32_e32 v69, v69
	v_exp_f32_e32 v66, v66
	v_exp_f32_e32 v70, v70
	v_exp_f32_e32 v67, v67
	v_exp_f32_e32 v71, v71
	v_cmp_le_i32_e32 vcc, v112, v113
	v_cmp_le_i32_e64 s[2:3], v112, v158
	s_nop 0
	v_cndmask_b32_e32 v64, 0, v64, vcc
	v_cndmask_b32_e64 v68, 0, v68, s[2:3]
	v_cmp_lt_i32_e32 vcc, v112, v113
	v_cmp_lt_i32_e64 s[2:3], v112, v158
	s_nop 0
	v_cndmask_b32_e32 v65, 0, v65, vcc
	v_cndmask_b32_e64 v69, 0, v69, s[2:3]
	v_cmp_le_i32_e32 vcc, v86, v113
	v_cmp_le_i32_e64 s[2:3], v86, v158
	s_nop 0
	v_cndmask_b32_e32 v66, 0, v66, vcc
	v_cndmask_b32_e64 v70, 0, v70, s[2:3]
	v_cmp_le_i32_e32 vcc, v88, v113
	v_cmp_le_i32_e64 s[2:3], v88, v158
	s_nop 0
	v_cndmask_b32_e32 v67, 0, v67, vcc
	v_cndmask_b32_e64 v71, 0, v71, s[2:3]
	v_add_f32_e32 v162, v64, v65
	v_add_f32_e32 v163, v68, v69
	v_add_f32_e32 v162, v66, v162
	v_add_f32_e32 v163, v70, v163
	v_mul_f32_e32 v246, 0.5, v67
	v_mul_f32_e32 v247, 0.5, v71
	v_fmac_f32_e32 v162, 0.5, v67
	v_fmac_f32_e32 v163, 0.5, v71
	s_nop 1
	v_add_f32_dpp v162, v162, v162 quad_perm:[1,0,3,2] row_mask:0xf bank_mask:0xf
	v_add_f32_dpp v163, v163, v163 quad_perm:[1,0,3,2] row_mask:0xf bank_mask:0xf
	v_add_f32_dpp v246, v246, v246 quad_perm:[1,0,3,2] row_mask:0xf bank_mask:0xf
	v_add_f32_dpp v247, v247, v247 quad_perm:[1,0,3,2] row_mask:0xf bank_mask:0xf
	v_add_f32_dpp v162, v162, v162 quad_perm:[2,3,0,1] row_mask:0xf bank_mask:0xf
	v_add_f32_dpp v163, v163, v163 quad_perm:[2,3,0,1] row_mask:0xf bank_mask:0xf
	v_add_f32_dpp v246, v246, v246 quad_perm:[2,3,0,1] row_mask:0xf bank_mask:0xf
	v_add_f32_dpp v247, v247, v247 quad_perm:[2,3,0,1] row_mask:0xf bank_mask:0xf
	s_and_saveexec_b64 s[40:41], s[4:5]
	ds_write_b32 v161, v162
	s_waitcnt lgkmcnt(13)
	ds_write_b32 v160, v246
	ds_write_b32 v159, v163
	s_waitcnt lgkmcnt(13)
	ds_write_b32 v160, v247 offset:1040
	s_mov_b64 exec, s[40:41]
	v_add_f32_e32 v72, v186, v72
	v_add_f32_e32 v226, v187, v226
	v_add_f32_e32 v73, v186, v73
	v_add_f32_e32 v227, v187, v227
	v_add_f32_e32 v74, v186, v74
	v_add_f32_e32 v228, v187, v228
	v_add_f32_e32 v75, v186, v75
	v_add_f32_e32 v229, v187, v229
	v_exp_f32_e32 v72, v72
	v_exp_f32_e32 v226, v226
	v_exp_f32_e32 v73, v73
	v_exp_f32_e32 v227, v227
	v_exp_f32_e32 v74, v74
	v_exp_f32_e32 v228, v228
	v_exp_f32_e32 v75, v75
	v_exp_f32_e32 v229, v229
	v_cmp_le_i32_e32 vcc, v90, v113
	v_cmp_le_i32_e64 s[2:3], v90, v158
	s_nop 0
	v_cndmask_b32_e32 v72, 0, v72, vcc
	v_cndmask_b32_e64 v226, 0, v226, s[2:3]
	v_cmp_le_i32_e32 vcc, v92, v113
	v_cmp_le_i32_e64 s[2:3], v92, v158
	s_nop 0
	v_cndmask_b32_e32 v73, 0, v73, vcc
	v_cndmask_b32_e64 v227, 0, v227, s[2:3]
	v_cmp_le_i32_e32 vcc, v94, v113
	v_cmp_le_i32_e64 s[2:3], v94, v158
	s_nop 0
	v_cndmask_b32_e32 v74, 0, v74, vcc
	v_cndmask_b32_e64 v228, 0, v228, s[2:3]
	v_cmp_le_i32_e32 vcc, v96, v113
	v_cmp_le_i32_e64 s[2:3], v96, v158
	s_nop 0
	v_cndmask_b32_e32 v75, 0, v75, vcc
	v_cndmask_b32_e64 v229, 0, v229, s[2:3]
	v_add_f32_e32 v162, v72, v73
	v_add_f32_e32 v163, v226, v227
	v_add_f32_e32 v162, v74, v162
	v_add_f32_e32 v163, v228, v163
	v_mul_f32_e32 v246, 0.5, v75
	v_mul_f32_e32 v247, 0.5, v229
	v_fmac_f32_e32 v162, 0.5, v75
	v_fmac_f32_e32 v163, 0.5, v229
	s_nop 1
	v_add_f32_dpp v162, v162, v162 quad_perm:[1,0,3,2] row_mask:0xf bank_mask:0xf
	v_add_f32_dpp v163, v163, v163 quad_perm:[1,0,3,2] row_mask:0xf bank_mask:0xf
	v_add_f32_dpp v246, v246, v246 quad_perm:[1,0,3,2] row_mask:0xf bank_mask:0xf
	v_add_f32_dpp v247, v247, v247 quad_perm:[1,0,3,2] row_mask:0xf bank_mask:0xf
	v_add_f32_dpp v162, v162, v162 quad_perm:[2,3,0,1] row_mask:0xf bank_mask:0xf
	v_add_f32_dpp v163, v163, v163 quad_perm:[2,3,0,1] row_mask:0xf bank_mask:0xf
	v_add_f32_dpp v246, v246, v246 quad_perm:[2,3,0,1] row_mask:0xf bank_mask:0xf
	v_add_f32_dpp v247, v247, v247 quad_perm:[2,3,0,1] row_mask:0xf bank_mask:0xf
	s_and_saveexec_b64 s[40:41], s[4:5]
	ds_write_b32 v161, v162 offset:16
	s_waitcnt lgkmcnt(13)
	ds_write_b32 v160, v246 offset:16
	ds_write_b32 v159, v163 offset:16
	s_waitcnt lgkmcnt(13)
	ds_write_b32 v160, v247 offset:1056
	s_mov_b64 exec, s[40:41]
	v_cvt_pk_bf16_f32 v64, v64, v65
	v_cvt_pk_bf16_f32 v65, v66, v67
	v_cvt_pk_bf16_f32 v66, v72, v73
	v_cvt_pk_bf16_f32 v67, v74, v75
	v_cvt_pk_bf16_f32 v68, v68, v69
	v_cvt_pk_bf16_f32 v69, v70, v71
	v_cvt_pk_bf16_f32 v70, v226, v227
	v_cvt_pk_bf16_f32 v71, v228, v229
	s_waitcnt lgkmcnt(0)
	s_barrier
	v_add_f32_e32 v230, v186, v230
	v_add_f32_e32 v234, v187, v234
	v_add_f32_e32 v231, v186, v231
	v_add_f32_e32 v235, v187, v235
	v_add_f32_e32 v232, v186, v232
	v_add_f32_e32 v236, v187, v236
	v_add_f32_e32 v233, v186, v233
	v_add_f32_e32 v237, v187, v237
	v_exp_f32_e32 v230, v230
	v_exp_f32_e32 v234, v234
	v_exp_f32_e32 v231, v231
	v_exp_f32_e32 v235, v235
	v_exp_f32_e32 v232, v232
	v_exp_f32_e32 v236, v236
	v_mfma_f32_16x16x32_bf16 v[60:63], v[190:193], v[64:67], v[60:63]
	v_exp_f32_e32 v233, v233
	v_exp_f32_e32 v237, v237
	v_cmp_le_i32_e32 vcc, v98, v113
	v_cmp_le_i32_e64 s[2:3], v98, v158
	s_nop 0
	v_cndmask_b32_e32 v230, 0, v230, vcc
	v_cndmask_b32_e64 v234, 0, v234, s[2:3]
	v_cmp_le_i32_e32 vcc, v100, v113
	v_cmp_le_i32_e64 s[2:3], v100, v158
	s_nop 0
	v_cndmask_b32_e32 v231, 0, v231, vcc
	v_cndmask_b32_e64 v235, 0, v235, s[2:3]
	v_cmp_le_i32_e32 vcc, v102, v113
	v_cmp_le_i32_e64 s[2:3], v102, v158
	v_mfma_f32_16x16x32_bf16 v[44:47], v[190:193], v[68:71], v[44:47]
	s_nop 0
	v_cndmask_b32_e32 v232, 0, v232, vcc
	v_cndmask_b32_e64 v236, 0, v236, s[2:3]
	v_cmp_le_i32_e32 vcc, v120, v113
	v_cmp_le_i32_e64 s[2:3], v120, v158
	s_nop 0
	v_cndmask_b32_e32 v233, 0, v233, vcc
	v_cndmask_b32_e64 v237, 0, v237, s[2:3]
	v_add_f32_e32 v162, v230, v231
	v_add_f32_e32 v163, v234, v235
	v_add_f32_e32 v162, v232, v162
	v_add_f32_e32 v163, v236, v163
	v_mul_f32_e32 v246, 0.5, v233
	v_mul_f32_e32 v247, 0.5, v237
	v_mfma_f32_16x16x32_bf16 v[56:59], v[194:197], v[64:67], v[56:59]
	v_fmac_f32_e32 v162, 0.5, v233
	v_fmac_f32_e32 v163, 0.5, v237
	s_nop 1
	v_add_f32_dpp v162, v162, v162 quad_perm:[1,0,3,2] row_mask:0xf bank_mask:0xf
	v_add_f32_dpp v163, v163, v163 quad_perm:[1,0,3,2] row_mask:0xf bank_mask:0xf
	v_add_f32_dpp v246, v246, v246 quad_perm:[1,0,3,2] row_mask:0xf bank_mask:0xf
	v_add_f32_dpp v247, v247, v247 quad_perm:[1,0,3,2] row_mask:0xf bank_mask:0xf
	v_add_f32_dpp v162, v162, v162 quad_perm:[2,3,0,1] row_mask:0xf bank_mask:0xf
	v_add_f32_dpp v163, v163, v163 quad_perm:[2,3,0,1] row_mask:0xf bank_mask:0xf
	v_add_f32_dpp v246, v246, v246 quad_perm:[2,3,0,1] row_mask:0xf bank_mask:0xf
	v_add_f32_dpp v247, v247, v247 quad_perm:[2,3,0,1] row_mask:0xf bank_mask:0xf
	s_and_saveexec_b64 s[40:41], s[4:5]
	ds_write_b32 v161, v162 offset:32
	ds_write_b32 v160, v246 offset:32
	ds_write_b32 v159, v163 offset:32
	ds_write_b32 v160, v247 offset:1072
	s_mov_b64 exec, s[40:41]
	v_add_f32_e32 v238, v186, v238
	v_add_f32_e32 v242, v187, v242
	v_mfma_f32_16x16x32_bf16 v[40:43], v[194:197], v[68:71], v[40:43]
	v_add_f32_e32 v239, v186, v239
	v_add_f32_e32 v243, v187, v243
	v_add_f32_e32 v240, v186, v240
	v_add_f32_e32 v244, v187, v244
	v_add_f32_e32 v241, v186, v241
	v_add_f32_e32 v245, v187, v245
	v_exp_f32_e32 v238, v238
	v_exp_f32_e32 v242, v242
	v_exp_f32_e32 v239, v239
	v_exp_f32_e32 v243, v243
	v_exp_f32_e32 v240, v240
	v_exp_f32_e32 v244, v244
	v_exp_f32_e32 v241, v241
	v_exp_f32_e32 v245, v245
	v_mfma_f32_16x16x32_bf16 v[52:55], v[198:201], v[64:67], v[52:55]
	v_cmp_le_i32_e32 vcc, v122, v113
	v_cmp_le_i32_e64 s[2:3], v122, v158
	s_nop 0
	v_cndmask_b32_e32 v238, 0, v238, vcc
	v_cndmask_b32_e64 v242, 0, v242, s[2:3]
	v_cmp_le_i32_e32 vcc, v124, v113
	v_cmp_le_i32_e64 s[2:3], v124, v158
	s_nop 0
	v_cndmask_b32_e32 v239, 0, v239, vcc
	v_cndmask_b32_e64 v243, 0, v243, s[2:3]
	v_cmp_le_i32_e32 vcc, v126, v113
	v_cmp_le_i32_e64 s[2:3], v126, v158
	s_nop 0
	v_cndmask_b32_e32 v240, 0, v240, vcc
	v_mfma_f32_16x16x32_bf16 v[36:39], v[198:201], v[68:71], v[36:39]
	v_cndmask_b32_e64 v244, 0, v244, s[2:3]
	v_cmp_le_i32_e32 vcc, v128, v113
	v_cmp_le_i32_e64 s[2:3], v128, v158
	s_nop 0
	v_cndmask_b32_e32 v241, 0, v241, vcc
	v_cndmask_b32_e64 v245, 0, v245, s[2:3]
	v_add_f32_e32 v162, v238, v239
	v_add_f32_e32 v163, v242, v243
	v_add_f32_e32 v162, v240, v162
	v_add_f32_e32 v163, v244, v163
	v_mul_f32_e32 v246, 0.5, v241
	v_mul_f32_e32 v247, 0.5, v245
	v_fmac_f32_e32 v162, 0.5, v241
	v_fmac_f32_e32 v163, 0.5, v245
	v_mfma_f32_16x16x32_bf16 v[48:51], v[202:205], v[64:67], v[48:51]
	s_nop 1
	v_add_f32_dpp v162, v162, v162 quad_perm:[1,0,3,2] row_mask:0xf bank_mask:0xf
	v_add_f32_dpp v163, v163, v163 quad_perm:[1,0,3,2] row_mask:0xf bank_mask:0xf
	v_add_f32_dpp v246, v246, v246 quad_perm:[1,0,3,2] row_mask:0xf bank_mask:0xf
	v_add_f32_dpp v247, v247, v247 quad_perm:[1,0,3,2] row_mask:0xf bank_mask:0xf
	v_add_f32_dpp v162, v162, v162 quad_perm:[2,3,0,1] row_mask:0xf bank_mask:0xf
	v_add_f32_dpp v163, v163, v163 quad_perm:[2,3,0,1] row_mask:0xf bank_mask:0xf
	v_add_f32_dpp v246, v246, v246 quad_perm:[2,3,0,1] row_mask:0xf bank_mask:0xf
	v_add_f32_dpp v247, v247, v247 quad_perm:[2,3,0,1] row_mask:0xf bank_mask:0xf
	s_and_saveexec_b64 s[40:41], s[4:5]
	ds_write_b32 v161, v162 offset:48
	ds_write_b32 v160, v246 offset:48
	ds_write_b32 v159, v163 offset:48
	ds_write_b32 v160, v247 offset:1088
	s_mov_b64 exec, s[40:41]
	v_cvt_pk_bf16_f32 v230, v230, v231
	v_cvt_pk_bf16_f32 v231, v232, v233
	v_cvt_pk_bf16_f32 v232, v238, v239
	v_cvt_pk_bf16_f32 v233, v240, v241
	v_mfma_f32_16x16x32_bf16 v[32:35], v[202:205], v[68:71], v[32:35]
	v_cvt_pk_bf16_f32 v234, v234, v235
	v_cvt_pk_bf16_f32 v235, v236, v237
	v_cvt_pk_bf16_f32 v236, v242, v243
	v_cvt_pk_bf16_f32 v237, v244, v245
	v_add_u32_e32 v159, 64, v159
	v_add_u32_e32 v160, 64, v160
	v_add_u32_e32 v161, 64, v161
	v_subrev_u32_e32 v158, 64, v158
	v_subrev_u32_e32 v113, 64, v113
	s_add_i32 s33, s33, 1
	s_add_i32 s2, s39, s33
	s_waitcnt lgkmcnt(0)
	ds_read_b128 v[190:193], v188 offset:0
	ds_read_b128 v[194:197], v188 offset:64
	ds_read_b128 v[198:201], v188 offset:2304
	ds_read_b128 v[202:205], v188 offset:2368
	s_setprio 2
	v_mfma_f32_16x16x32_bf16 v[60:63], v[206:209], v[230:233], v[60:63]
	v_mfma_f32_16x16x32_bf16 v[44:47], v[206:209], v[234:237], v[44:47]
	v_mfma_f32_16x16x32_bf16 v[56:59], v[210:213], v[230:233], v[56:59]
	v_mfma_f32_16x16x32_bf16 v[40:43], v[210:213], v[234:237], v[40:43]
	v_mfma_f32_16x16x32_bf16 v[52:55], v[218:221], v[230:233], v[52:55]
	v_mfma_f32_16x16x32_bf16 v[36:39], v[218:221], v[234:237], v[36:39]
	v_mfma_f32_16x16x32_bf16 v[48:51], v[222:225], v[230:233], v[48:51]
	v_mfma_f32_16x16x32_bf16 v[32:35], v[222:225], v[234:237], v[32:35]
	s_cmp_lg_u32 s2, 2
	s_cbranch_scc1 .LBB0_838
.Lcmpb_done:
	s_waitcnt lgkmcnt(0)
	s_setprio 1
.LBB0_854:
	s_mov_b32 s2, s58
	v_writelane_b32 v250, s2, 40
	s_lshr_b32 s33, s58, 1
	s_waitcnt vmcnt(2)
	v_lshlrev_b64 v[16:17], 11, v[152:153]
	v_writelane_b32 v250, s3, 41
	v_lshlrev_b32_e32 v18, 7, v145
	v_readlane_b32 s48, v250, 24
	v_readlane_b32 s49, v250, 25
	v_readlane_b32 s60, v250, 36
	v_readlane_b32 s61, v250, 37
	s_mov_b64 s[48:49], s[60:61]
	v_lshl_add_u64 v[16:17], s[48:49], 0, v[16:17]
	v_mov_b32_e32 v19, v117
	v_lshl_add_u64 v[16:17], v[16:17], 0, v[18:19]
	v_lshlrev_b32_e32 v152, 1, v130
	v_mov_b32_e32 v153, v117
	v_lshl_add_u64 v[154:155], v[16:17], 0, v[152:153]
	v_mul_f32_e32 v16, v80, v60
	v_mul_f32_e32 v17, v80, v61
	v_mul_f32_e32 v20, v80, v62
	v_mul_f32_e32 v21, v80, v63
	v_cvt_pk_bf16_f32 v16, v16, v17
	v_cvt_pk_bf16_f32 v17, v20, v21
	global_store_dwordx2 v[154:155], v[16:17], off
	v_mul_f32_e32 v16, v80, v56
	v_mul_f32_e32 v17, v80, v57
	v_mul_f32_e32 v20, v80, v58
	v_mul_f32_e32 v21, v80, v59
	v_cvt_pk_bf16_f32 v16, v16, v17
	v_cvt_pk_bf16_f32 v17, v20, v21
	global_store_dwordx2 v[154:155], v[16:17], off offset:32
	v_mul_f32_e32 v16, v80, v52
	v_mul_f32_e32 v17, v80, v53
	v_mul_f32_e32 v20, v80, v54
	v_mul_f32_e32 v21, v80, v55
	v_cvt_pk_bf16_f32 v16, v16, v17
	v_cvt_pk_bf16_f32 v17, v20, v21
	global_store_dwordx2 v[154:155], v[16:17], off offset:64
	v_mul_f32_e32 v16, v80, v48
	v_mul_f32_e32 v17, v80, v49
	v_mul_f32_e32 v20, v80, v50
	v_mul_f32_e32 v21, v80, v51
	v_cvt_pk_bf16_f32 v16, v16, v17
	v_cvt_pk_bf16_f32 v17, v20, v21
	global_store_dwordx2 v[154:155], v[16:17], off offset:96
	v_lshlrev_b64 v[16:17], 11, v[150:151]
	v_lshl_add_u64 v[16:17], s[48:49], 0, v[16:17]
	v_lshl_add_u64 v[16:17], v[16:17], 0, v[18:19]
	v_lshl_add_u64 v[150:151], v[16:17], 0, v[152:153]
	v_mul_f32_e32 v16, v76, v44
	v_mul_f32_e32 v17, v76, v45
	v_cvt_pk_bf16_f32 v16, v16, v17
	v_mul_f32_e32 v18, v76, v46
	v_mul_f32_e32 v19, v76, v47
	v_cvt_pk_bf16_f32 v17, v18, v19
	global_store_dwordx2 v[150:151], v[16:17], off
	v_mul_f32_e32 v16, v76, v40
	v_mul_f32_e32 v17, v76, v41
	v_cvt_pk_bf16_f32 v16, v16, v17
	v_mul_f32_e32 v18, v76, v42
	v_mul_f32_e32 v19, v76, v43
	v_cvt_pk_bf16_f32 v17, v18, v19
	global_store_dwordx2 v[150:151], v[16:17], off offset:32
	v_mul_f32_e32 v16, v76, v36
	v_mul_f32_e32 v17, v76, v37
	v_cvt_pk_bf16_f32 v16, v16, v17
	v_readlane_b32 s40, v249, 12
	v_mul_f32_e32 v18, v76, v38
	v_mul_f32_e32 v19, v76, v39
	v_cvt_pk_bf16_f32 v17, v18, v19
	global_store_dwordx2 v[150:151], v[16:17], off offset:64
	v_mul_f32_e32 v16, v76, v32
	s_lshl_b32 s2, s38, 4
	v_cmp_eq_u32_e32 vcc, s33, v106
	v_readlane_b32 s41, v249, 13
	s_add_i32 s47, s33, -1
	v_mul_f32_e32 v17, v76, v33
	v_cvt_pk_bf16_f32 v16, v16, v17
	s_add_i32 s2, s2, 16
	s_or_b64 s[40:41], s[40:41], vcc
	v_cmp_eq_u32_e32 vcc, s47, v106
	v_mul_f32_e32 v18, v76, v34
	v_mul_f32_e32 v19, v76, v35
	v_cvt_pk_bf16_f32 v17, v18, v19
	global_store_dwordx2 v[150:151], v[16:17], off offset:96
	v_cmp_gt_u32_e64 s[38:39], s2, v106
	v_cmp_gt_u32_e64 s[2:3], s2, v166
	s_or_b64 s[40:41], s[40:41], vcc
	v_lshl_add_u32 v16, v106, 2, s42
	v_mov_b64_e32 v[72:73], 0
	s_mov_b32 s44, 0
	s_mov_b32 s48, 0x9800
	v_readlane_b32 s50, v250, 26
	v_readlane_b32 s51, v250, 27
	v_readlane_b32 s52, v250, 28
	v_readlane_b32 s53, v250, 29
	v_readlane_b32 s54, v250, 30
	v_readlane_b32 s55, v250, 31
	v_readlane_b32 s56, v250, 32
	v_readlane_b32 s57, v250, 33
	v_readlane_b32 s58, v250, 34
	v_readlane_b32 s59, v250, 35
	v_readlane_b32 s62, v250, 38
	v_readlane_b32 s63, v250, 39
	v_mov_b32_e32 v20, 0
	v_mov_b32_e32 v19, 0
	s_and_saveexec_b64 s[42:43], s[38:39]
	ds_read_b32 v20, v16 offset:37632
	s_mov_b64 exec, s[42:43]
	s_and_saveexec_b64 s[42:43], s[2:3]
	ds_read_b32 v19, v16 offset:39692
	s_mov_b64 exec, s[42:43]
	s_add_i32 s84, s46, 3
	s_waitcnt lgkmcnt(0)
	v_add_f32_e32 v20, v20, v19
	v_cmp_ge_u32_e32 vcc, s84, v165
	v_cndmask_b32_e64 v20, v20, v180, s[40:41]
	s_nop 1
	v_cndmask_b32_e32 v20, v181, v20, vcc
	v_ashrrev_i32_e32 v19, 31, v20
	v_or_b32_e32 v19, 0x80000000, v19
	v_xor_b32_e32 v20, v19, v20
	v_mov_b32_e32 v19, 0
	v_mov_b32_e32 v18, 0
	s_and_saveexec_b64 s[42:43], s[38:39]
	ds_read_b32 v19, v16 offset:37376
	s_mov_b64 exec, s[42:43]
	s_and_saveexec_b64 s[42:43], s[2:3]
	ds_read_b32 v18, v16 offset:39432
	s_mov_b64 exec, s[42:43]
	s_add_i32 s84, s46, 2
	s_waitcnt lgkmcnt(0)
	v_add_f32_e32 v19, v19, v18
	v_cmp_ge_u32_e32 vcc, s84, v165
	v_cndmask_b32_e64 v19, v19, v180, s[40:41]
	s_nop 1
	v_cndmask_b32_e32 v19, v181, v19, vcc
	v_ashrrev_i32_e32 v18, 31, v19
	v_or_b32_e32 v18, 0x80000000, v18
	v_xor_b32_e32 v19, v18, v19
	v_mov_b32_e32 v18, 0
	v_mov_b32_e32 v17, 0
	s_and_saveexec_b64 s[42:43], s[38:39]
	ds_read_b32 v18, v16 offset:37120
	s_mov_b64 exec, s[42:43]
	s_and_saveexec_b64 s[42:43], s[2:3]
	ds_read_b32 v17, v16 offset:39172
	s_mov_b64 exec, s[42:43]
	s_add_i32 s84, s46, 1
	s_waitcnt lgkmcnt(0)
	v_add_f32_e32 v18, v18, v17
	v_cmp_ge_u32_e32 vcc, s84, v165
	v_cndmask_b32_e64 v18, v18, v180, s[40:41]
	s_nop 1
	v_cndmask_b32_e32 v18, v181, v18, vcc
	v_ashrrev_i32_e32 v17, 31, v18
	v_or_b32_e32 v17, 0x80000000, v17
	v_xor_b32_e32 v18, v17, v18
	v_mov_b32_e32 v17, 0
	v_mov_b32_e32 v73, 0
	s_and_saveexec_b64 s[42:43], s[38:39]
	ds_read_b32 v17, v16 offset:36864
	s_mov_b64 exec, s[42:43]
	s_and_saveexec_b64 s[42:43], s[2:3]
	ds_read_b32 v73, v16 offset:38912
	s_mov_b64 exec, s[42:43]
	s_add_i32 s84, s46, 0
	s_waitcnt lgkmcnt(0)
	v_add_f32_e32 v17, v17, v73
	v_cmp_ge_u32_e32 vcc, s84, v165
	v_cndmask_b32_e64 v17, v17, v180, s[40:41]
	s_nop 1
	v_cndmask_b32_e32 v17, v181, v17, vcc
	v_ashrrev_i32_e32 v73, 31, v17
	v_or_b32_e32 v73, 0x80000000, v73
	v_xor_b32_e32 v17, v73, v17
	v_mov_b32_e32 v73, 0
	s_add_i32 s46, s46, 4
	s_mov_b32 s64, 0
	s_mov_b32 s65, 0
	s_mov_b32 s66, 0
	s_mov_b32 s67, 0
	s_mov_b32 s94, 0
	s_mov_b32 s95, 0
	s_mov_b32 s96, 0
	s_mov_b32 s97, 0
	s_or_b32 s68, s64, 0x80000000
	s_or_b32 s69, s65, 0x80000000
	s_or_b32 s70, s66, 0x80000000
	s_or_b32 s71, s67, 0x80000000
	v_cmp_le_u32_e64 s[76:77], s68, v17
	v_cmp_le_u32_e64 s[78:79], s69, v18
	v_cmp_le_u32_e64 s[80:81], s70, v19
	v_cmp_le_u32_e64 s[82:83], s71, v20
	s_bcnt1_i32_b64 s72, s[76:77]
	s_bcnt1_i32_b64 s73, s[78:79]
	s_bcnt1_i32_b64 s74, s[80:81]
	s_bcnt1_i32_b64 s75, s[82:83]
	s_cmp_ge_u32 s72, 16
	s_cselect_b32 s64, s68, s64
	s_cselect_b32 s94, s72, s94
	s_cmp_ge_u32 s73, 16
	s_cselect_b32 s65, s69, s65
	s_cselect_b32 s95, s73, s95
	s_cmp_ge_u32 s74, 16
	s_cselect_b32 s66, s70, s66
	s_cselect_b32 s96, s74, s96
	s_cmp_ge_u32 s75, 16
	s_cselect_b32 s67, s71, s67
	s_cselect_b32 s97, s75, s97
	s_or_b32 s68, s64, 0x40000000
	s_or_b32 s69, s65, 0x40000000
	s_or_b32 s70, s66, 0x40000000
	s_or_b32 s71, s67, 0x40000000
	v_cmp_le_u32_e64 s[76:77], s68, v17
	v_cmp_le_u32_e64 s[78:79], s69, v18
	v_cmp_le_u32_e64 s[80:81], s70, v19
	v_cmp_le_u32_e64 s[82:83], s71, v20
	s_bcnt1_i32_b64 s72, s[76:77]
	s_bcnt1_i32_b64 s73, s[78:79]
	s_bcnt1_i32_b64 s74, s[80:81]
	s_bcnt1_i32_b64 s75, s[82:83]
	s_cmp_ge_u32 s72, 16
	s_cselect_b32 s64, s68, s64
	s_cselect_b32 s94, s72, s94
	s_cmp_ge_u32 s73, 16
	s_cselect_b32 s65, s69, s65
	s_cselect_b32 s95, s73, s95
	s_cmp_ge_u32 s74, 16
	s_cselect_b32 s66, s70, s66
	s_cselect_b32 s96, s74, s96
	s_cmp_ge_u32 s75, 16
	s_cselect_b32 s67, s71, s67
	s_cselect_b32 s97, s75, s97
	s_xor_b32 s84, s94, 16
	s_xor_b32 s85, s95, 16
	s_or_b32 s84, s84, s85
	s_xor_b32 s85, s96, 16
	s_or_b32 s84, s84, s85
	s_xor_b32 s85, s97, 16
	s_or_b32 s84, s84, s85
	s_cmp_eq_u32 s84, 0
	s_cbranch_scc1 .Lrk1_found
	s_or_b32 s68, s64, 0x20000000
	s_or_b32 s69, s65, 0x20000000
	s_or_b32 s70, s66, 0x20000000
	s_or_b32 s71, s67, 0x20000000
	v_cmp_le_u32_e64 s[76:77], s68, v17
	v_cmp_le_u32_e64 s[78:79], s69, v18
	v_cmp_le_u32_e64 s[80:81], s70, v19
	v_cmp_le_u32_e64 s[82:83], s71, v20
	s_bcnt1_i32_b64 s72, s[76:77]
	s_bcnt1_i32_b64 s73, s[78:79]
	s_bcnt1_i32_b64 s74, s[80:81]
	s_bcnt1_i32_b64 s75, s[82:83]
	s_cmp_ge_u32 s72, 16
	s_cselect_b32 s64, s68, s64
	s_cselect_b32 s94, s72, s94
	s_cmp_ge_u32 s73, 16
	s_cselect_b32 s65, s69, s65
	s_cselect_b32 s95, s73, s95
	s_cmp_ge_u32 s74, 16
	s_cselect_b32 s66, s70, s66
	s_cselect_b32 s96, s74, s96
	s_cmp_ge_u32 s75, 16
	s_cselect_b32 s67, s71, s67
	s_cselect_b32 s97, s75, s97
	s_or_b32 s68, s64, 0x10000000
	s_or_b32 s69, s65, 0x10000000
	s_or_b32 s70, s66, 0x10000000
	s_or_b32 s71, s67, 0x10000000
	v_cmp_le_u32_e64 s[76:77], s68, v17
	v_cmp_le_u32_e64 s[78:79], s69, v18
	v_cmp_le_u32_e64 s[80:81], s70, v19
	v_cmp_le_u32_e64 s[82:83], s71, v20
	s_bcnt1_i32_b64 s72, s[76:77]
	s_bcnt1_i32_b64 s73, s[78:79]
	s_bcnt1_i32_b64 s74, s[80:81]
	s_bcnt1_i32_b64 s75, s[82:83]
	s_cmp_ge_u32 s72, 16
	s_cselect_b32 s64, s68, s64
	s_cselect_b32 s94, s72, s94
	s_cmp_ge_u32 s73, 16
	s_cselect_b32 s65, s69, s65
	s_cselect_b32 s95, s73, s95
	s_cmp_ge_u32 s74, 16
	s_cselect_b32 s66, s70, s66
	s_cselect_b32 s96, s74, s96
	s_cmp_ge_u32 s75, 16
	s_cselect_b32 s67, s71, s67
	s_cselect_b32 s97, s75, s97
	s_xor_b32 s84, s94, 16
	s_xor_b32 s85, s95, 16
	s_or_b32 s84, s84, s85
	s_xor_b32 s85, s96, 16
	s_or_b32 s84, s84, s85
	s_xor_b32 s85, s97, 16
	s_or_b32 s84, s84, s85
	s_cmp_eq_u32 s84, 0
	s_cbranch_scc1 .Lrk1_found
	s_or_b32 s68, s64, 0x8000000
	s_or_b32 s69, s65, 0x8000000
	s_or_b32 s70, s66, 0x8000000
	s_or_b32 s71, s67, 0x8000000
	v_cmp_le_u32_e64 s[76:77], s68, v17
	v_cmp_le_u32_e64 s[78:79], s69, v18
	v_cmp_le_u32_e64 s[80:81], s70, v19
	v_cmp_le_u32_e64 s[82:83], s71, v20
	s_bcnt1_i32_b64 s72, s[76:77]
	s_bcnt1_i32_b64 s73, s[78:79]
	s_bcnt1_i32_b64 s74, s[80:81]
	s_bcnt1_i32_b64 s75, s[82:83]
	s_cmp_ge_u32 s72, 16
	s_cselect_b32 s64, s68, s64
	s_cselect_b32 s94, s72, s94
	s_cmp_ge_u32 s73, 16
	s_cselect_b32 s65, s69, s65
	s_cselect_b32 s95, s73, s95
	s_cmp_ge_u32 s74, 16
	s_cselect_b32 s66, s70, s66
	s_cselect_b32 s96, s74, s96
	s_cmp_ge_u32 s75, 16
	s_cselect_b32 s67, s71, s67
	s_cselect_b32 s97, s75, s97
	s_or_b32 s68, s64, 0x4000000
	s_or_b32 s69, s65, 0x4000000
	s_or_b32 s70, s66, 0x4000000
	s_or_b32 s71, s67, 0x4000000
	v_cmp_le_u32_e64 s[76:77], s68, v17
	v_cmp_le_u32_e64 s[78:79], s69, v18
	v_cmp_le_u32_e64 s[80:81], s70, v19
	v_cmp_le_u32_e64 s[82:83], s71, v20
	s_bcnt1_i32_b64 s72, s[76:77]
	s_bcnt1_i32_b64 s73, s[78:79]
	s_bcnt1_i32_b64 s74, s[80:81]
	s_bcnt1_i32_b64 s75, s[82:83]
	s_cmp_ge_u32 s72, 16
	s_cselect_b32 s64, s68, s64
	s_cselect_b32 s94, s72, s94
	s_cmp_ge_u32 s73, 16
	s_cselect_b32 s65, s69, s65
	s_cselect_b32 s95, s73, s95
	s_cmp_ge_u32 s74, 16
	s_cselect_b32 s66, s70, s66
	s_cselect_b32 s96, s74, s96
	s_cmp_ge_u32 s75, 16
	s_cselect_b32 s67, s71, s67
	s_cselect_b32 s97, s75, s97
	s_xor_b32 s84, s94, 16
	s_xor_b32 s85, s95, 16
	s_or_b32 s84, s84, s85
	s_xor_b32 s85, s96, 16
	s_or_b32 s84, s84, s85
	s_xor_b32 s85, s97, 16
	s_or_b32 s84, s84, s85
	s_cmp_eq_u32 s84, 0
	s_cbranch_scc1 .Lrk1_found
	s_or_b32 s68, s64, 0x2000000
	s_or_b32 s69, s65, 0x2000000
	s_or_b32 s70, s66, 0x2000000
	s_or_b32 s71, s67, 0x2000000
	v_cmp_le_u32_e64 s[76:77], s68, v17
	v_cmp_le_u32_e64 s[78:79], s69, v18
	v_cmp_le_u32_e64 s[80:81], s70, v19
	v_cmp_le_u32_e64 s[82:83], s71, v20
	s_bcnt1_i32_b64 s72, s[76:77]
	s_bcnt1_i32_b64 s73, s[78:79]
	s_bcnt1_i32_b64 s74, s[80:81]
	s_bcnt1_i32_b64 s75, s[82:83]
	s_cmp_ge_u32 s72, 16
	s_cselect_b32 s64, s68, s64
	s_cselect_b32 s94, s72, s94
	s_cmp_ge_u32 s73, 16
	s_cselect_b32 s65, s69, s65
	s_cselect_b32 s95, s73, s95
	s_cmp_ge_u32 s74, 16
	s_cselect_b32 s66, s70, s66
	s_cselect_b32 s96, s74, s96
	s_cmp_ge_u32 s75, 16
	s_cselect_b32 s67, s71, s67
	s_cselect_b32 s97, s75, s97
	s_or_b32 s68, s64, 0x1000000
	s_or_b32 s69, s65, 0x1000000
	s_or_b32 s70, s66, 0x1000000
	s_or_b32 s71, s67, 0x1000000
	v_cmp_le_u32_e64 s[76:77], s68, v17
	v_cmp_le_u32_e64 s[78:79], s69, v18
	v_cmp_le_u32_e64 s[80:81], s70, v19
	v_cmp_le_u32_e64 s[82:83], s71, v20
	s_bcnt1_i32_b64 s72, s[76:77]
	s_bcnt1_i32_b64 s73, s[78:79]
	s_bcnt1_i32_b64 s74, s[80:81]
	s_bcnt1_i32_b64 s75, s[82:83]
	s_cmp_ge_u32 s72, 16
	s_cselect_b32 s64, s68, s64
	s_cselect_b32 s94, s72, s94
	s_cmp_ge_u32 s73, 16
	s_cselect_b32 s65, s69, s65
	s_cselect_b32 s95, s73, s95
	s_cmp_ge_u32 s74, 16
	s_cselect_b32 s66, s70, s66
	s_cselect_b32 s96, s74, s96
	s_cmp_ge_u32 s75, 16
	s_cselect_b32 s67, s71, s67
	s_cselect_b32 s97, s75, s97
	s_xor_b32 s84, s94, 16
	s_xor_b32 s85, s95, 16
	s_or_b32 s84, s84, s85
	s_xor_b32 s85, s96, 16
	s_or_b32 s84, s84, s85
	s_xor_b32 s85, s97, 16
	s_or_b32 s84, s84, s85
	s_cmp_eq_u32 s84, 0
	s_cbranch_scc1 .Lrk1_found
	s_or_b32 s68, s64, 0x800000
	s_or_b32 s69, s65, 0x800000
	s_or_b32 s70, s66, 0x800000
	s_or_b32 s71, s67, 0x800000
	v_cmp_le_u32_e64 s[76:77], s68, v17
	v_cmp_le_u32_e64 s[78:79], s69, v18
	v_cmp_le_u32_e64 s[80:81], s70, v19
	v_cmp_le_u32_e64 s[82:83], s71, v20
	s_bcnt1_i32_b64 s72, s[76:77]
	s_bcnt1_i32_b64 s73, s[78:79]
	s_bcnt1_i32_b64 s74, s[80:81]
	s_bcnt1_i32_b64 s75, s[82:83]
	s_cmp_ge_u32 s72, 16
	s_cselect_b32 s64, s68, s64
	s_cselect_b32 s94, s72, s94
	s_cmp_ge_u32 s73, 16
	s_cselect_b32 s65, s69, s65
	s_cselect_b32 s95, s73, s95
	s_cmp_ge_u32 s74, 16
	s_cselect_b32 s66, s70, s66
	s_cselect_b32 s96, s74, s96
	s_cmp_ge_u32 s75, 16
	s_cselect_b32 s67, s71, s67
	s_cselect_b32 s97, s75, s97
	s_or_b32 s68, s64, 0x400000
	s_or_b32 s69, s65, 0x400000
	s_or_b32 s70, s66, 0x400000
	s_or_b32 s71, s67, 0x400000
	v_cmp_le_u32_e64 s[76:77], s68, v17
	v_cmp_le_u32_e64 s[78:79], s69, v18
	v_cmp_le_u32_e64 s[80:81], s70, v19
	v_cmp_le_u32_e64 s[82:83], s71, v20
	s_bcnt1_i32_b64 s72, s[76:77]
	s_bcnt1_i32_b64 s73, s[78:79]
	s_bcnt1_i32_b64 s74, s[80:81]
	s_bcnt1_i32_b64 s75, s[82:83]
	s_cmp_ge_u32 s72, 16
	s_cselect_b32 s64, s68, s64
	s_cselect_b32 s94, s72, s94
	s_cmp_ge_u32 s73, 16
	s_cselect_b32 s65, s69, s65
	s_cselect_b32 s95, s73, s95
	s_cmp_ge_u32 s74, 16
	s_cselect_b32 s66, s70, s66
	s_cselect_b32 s96, s74, s96
	s_cmp_ge_u32 s75, 16
	s_cselect_b32 s67, s71, s67
	s_cselect_b32 s97, s75, s97
	s_xor_b32 s84, s94, 16
	s_xor_b32 s85, s95, 16
	s_or_b32 s84, s84, s85
	s_xor_b32 s85, s96, 16
	s_or_b32 s84, s84, s85
	s_xor_b32 s85, s97, 16
	s_or_b32 s84, s84, s85
	s_cmp_eq_u32 s84, 0
	s_cbranch_scc1 .Lrk1_found
	s_or_b32 s68, s64, 0x200000
	s_or_b32 s69, s65, 0x200000
	s_or_b32 s70, s66, 0x200000
	s_or_b32 s71, s67, 0x200000
	v_cmp_le_u32_e64 s[76:77], s68, v17
	v_cmp_le_u32_e64 s[78:79], s69, v18
	v_cmp_le_u32_e64 s[80:81], s70, v19
	v_cmp_le_u32_e64 s[82:83], s71, v20
	s_bcnt1_i32_b64 s72, s[76:77]
	s_bcnt1_i32_b64 s73, s[78:79]
	s_bcnt1_i32_b64 s74, s[80:81]
	s_bcnt1_i32_b64 s75, s[82:83]
	s_cmp_ge_u32 s72, 16
	s_cselect_b32 s64, s68, s64
	s_cselect_b32 s94, s72, s94
	s_cmp_ge_u32 s73, 16
	s_cselect_b32 s65, s69, s65
	s_cselect_b32 s95, s73, s95
	s_cmp_ge_u32 s74, 16
	s_cselect_b32 s66, s70, s66
	s_cselect_b32 s96, s74, s96
	s_cmp_ge_u32 s75, 16
	s_cselect_b32 s67, s71, s67
	s_cselect_b32 s97, s75, s97
	s_or_b32 s68, s64, 0x100000
	s_or_b32 s69, s65, 0x100000
	s_or_b32 s70, s66, 0x100000
	s_or_b32 s71, s67, 0x100000
	v_cmp_le_u32_e64 s[76:77], s68, v17
	v_cmp_le_u32_e64 s[78:79], s69, v18
	v_cmp_le_u32_e64 s[80:81], s70, v19
	v_cmp_le_u32_e64 s[82:83], s71, v20
	s_bcnt1_i32_b64 s72, s[76:77]
	s_bcnt1_i32_b64 s73, s[78:79]
	s_bcnt1_i32_b64 s74, s[80:81]
	s_bcnt1_i32_b64 s75, s[82:83]
	s_cmp_ge_u32 s72, 16
	s_cselect_b32 s64, s68, s64
	s_cselect_b32 s94, s72, s94
	s_cmp_ge_u32 s73, 16
	s_cselect_b32 s65, s69, s65
	s_cselect_b32 s95, s73, s95
	s_cmp_ge_u32 s74, 16
	s_cselect_b32 s66, s70, s66
	s_cselect_b32 s96, s74, s96
	s_cmp_ge_u32 s75, 16
	s_cselect_b32 s67, s71, s67
	s_cselect_b32 s97, s75, s97
	s_xor_b32 s84, s94, 16
	s_xor_b32 s85, s95, 16
	s_or_b32 s84, s84, s85
	s_xor_b32 s85, s96, 16
	s_or_b32 s84, s84, s85
	s_xor_b32 s85, s97, 16
	s_or_b32 s84, s84, s85
	s_cmp_eq_u32 s84, 0
	s_cbranch_scc1 .Lrk1_found
	s_or_b32 s68, s64, 0x80000
	s_or_b32 s69, s65, 0x80000
	s_or_b32 s70, s66, 0x80000
	s_or_b32 s71, s67, 0x80000
	v_cmp_le_u32_e64 s[76:77], s68, v17
	v_cmp_le_u32_e64 s[78:79], s69, v18
	v_cmp_le_u32_e64 s[80:81], s70, v19
	v_cmp_le_u32_e64 s[82:83], s71, v20
	s_bcnt1_i32_b64 s72, s[76:77]
	s_bcnt1_i32_b64 s73, s[78:79]
	s_bcnt1_i32_b64 s74, s[80:81]
	s_bcnt1_i32_b64 s75, s[82:83]
	s_cmp_ge_u32 s72, 16
	s_cselect_b32 s64, s68, s64
	s_cselect_b32 s94, s72, s94
	s_cmp_ge_u32 s73, 16
	s_cselect_b32 s65, s69, s65
	s_cselect_b32 s95, s73, s95
	s_cmp_ge_u32 s74, 16
	s_cselect_b32 s66, s70, s66
	s_cselect_b32 s96, s74, s96
	s_cmp_ge_u32 s75, 16
	s_cselect_b32 s67, s71, s67
	s_cselect_b32 s97, s75, s97
	s_or_b32 s68, s64, 0x40000
	s_or_b32 s69, s65, 0x40000
	s_or_b32 s70, s66, 0x40000
	s_or_b32 s71, s67, 0x40000
	v_cmp_le_u32_e64 s[76:77], s68, v17
	v_cmp_le_u32_e64 s[78:79], s69, v18
	v_cmp_le_u32_e64 s[80:81], s70, v19
	v_cmp_le_u32_e64 s[82:83], s71, v20
	s_bcnt1_i32_b64 s72, s[76:77]
	s_bcnt1_i32_b64 s73, s[78:79]
	s_bcnt1_i32_b64 s74, s[80:81]
	s_bcnt1_i32_b64 s75, s[82:83]
	s_cmp_ge_u32 s72, 16
	s_cselect_b32 s64, s68, s64
	s_cselect_b32 s94, s72, s94
	s_cmp_ge_u32 s73, 16
	s_cselect_b32 s65, s69, s65
	s_cselect_b32 s95, s73, s95
	s_cmp_ge_u32 s74, 16
	s_cselect_b32 s66, s70, s66
	s_cselect_b32 s96, s74, s96
	s_cmp_ge_u32 s75, 16
	s_cselect_b32 s67, s71, s67
	s_cselect_b32 s97, s75, s97
	s_xor_b32 s84, s94, 16
	s_xor_b32 s85, s95, 16
	s_or_b32 s84, s84, s85
	s_xor_b32 s85, s96, 16
	s_or_b32 s84, s84, s85
	s_xor_b32 s85, s97, 16
	s_or_b32 s84, s84, s85
	s_cmp_eq_u32 s84, 0
	s_cbranch_scc1 .Lrk1_found
	s_or_b32 s68, s64, 0x20000
	s_or_b32 s69, s65, 0x20000
	s_or_b32 s70, s66, 0x20000
	s_or_b32 s71, s67, 0x20000
	v_cmp_le_u32_e64 s[76:77], s68, v17
	v_cmp_le_u32_e64 s[78:79], s69, v18
	v_cmp_le_u32_e64 s[80:81], s70, v19
	v_cmp_le_u32_e64 s[82:83], s71, v20
	s_bcnt1_i32_b64 s72, s[76:77]
	s_bcnt1_i32_b64 s73, s[78:79]
	s_bcnt1_i32_b64 s74, s[80:81]
	s_bcnt1_i32_b64 s75, s[82:83]
	s_cmp_ge_u32 s72, 16
	s_cselect_b32 s64, s68, s64
	s_cselect_b32 s94, s72, s94
	s_cmp_ge_u32 s73, 16
	s_cselect_b32 s65, s69, s65
	s_cselect_b32 s95, s73, s95
	s_cmp_ge_u32 s74, 16
	s_cselect_b32 s66, s70, s66
	s_cselect_b32 s96, s74, s96
	s_cmp_ge_u32 s75, 16
	s_cselect_b32 s67, s71, s67
	s_cselect_b32 s97, s75, s97
	s_or_b32 s68, s64, 0x10000
	s_or_b32 s69, s65, 0x10000
	s_or_b32 s70, s66, 0x10000
	s_or_b32 s71, s67, 0x10000
	v_cmp_le_u32_e64 s[76:77], s68, v17
	v_cmp_le_u32_e64 s[78:79], s69, v18
	v_cmp_le_u32_e64 s[80:81], s70, v19
	v_cmp_le_u32_e64 s[82:83], s71, v20
	s_bcnt1_i32_b64 s72, s[76:77]
	s_bcnt1_i32_b64 s73, s[78:79]
	s_bcnt1_i32_b64 s74, s[80:81]
	s_bcnt1_i32_b64 s75, s[82:83]
	s_cmp_ge_u32 s72, 16
	s_cselect_b32 s64, s68, s64
	s_cselect_b32 s94, s72, s94
	s_cmp_ge_u32 s73, 16
	s_cselect_b32 s65, s69, s65
	s_cselect_b32 s95, s73, s95
	s_cmp_ge_u32 s74, 16
	s_cselect_b32 s66, s70, s66
	s_cselect_b32 s96, s74, s96
	s_cmp_ge_u32 s75, 16
	s_cselect_b32 s67, s71, s67
	s_cselect_b32 s97, s75, s97
	s_xor_b32 s84, s94, 16
	s_xor_b32 s85, s95, 16
	s_or_b32 s84, s84, s85
	s_xor_b32 s85, s96, 16
	s_or_b32 s84, s84, s85
	s_xor_b32 s85, s97, 16
	s_or_b32 s84, s84, s85
	s_cmp_eq_u32 s84, 0
	s_cbranch_scc1 .Lrk1_found
	s_or_b32 s68, s64, 0x8000
	s_or_b32 s69, s65, 0x8000
	s_or_b32 s70, s66, 0x8000
	s_or_b32 s71, s67, 0x8000
	v_cmp_le_u32_e64 s[76:77], s68, v17
	v_cmp_le_u32_e64 s[78:79], s69, v18
	v_cmp_le_u32_e64 s[80:81], s70, v19
	v_cmp_le_u32_e64 s[82:83], s71, v20
	s_bcnt1_i32_b64 s72, s[76:77]
	s_bcnt1_i32_b64 s73, s[78:79]
	s_bcnt1_i32_b64 s74, s[80:81]
	s_bcnt1_i32_b64 s75, s[82:83]
	s_cmp_ge_u32 s72, 16
	s_cselect_b32 s64, s68, s64
	s_cselect_b32 s94, s72, s94
	s_cmp_ge_u32 s73, 16
	s_cselect_b32 s65, s69, s65
	s_cselect_b32 s95, s73, s95
	s_cmp_ge_u32 s74, 16
	s_cselect_b32 s66, s70, s66
	s_cselect_b32 s96, s74, s96
	s_cmp_ge_u32 s75, 16
	s_cselect_b32 s67, s71, s67
	s_cselect_b32 s97, s75, s97
	s_or_b32 s68, s64, 0x4000
	s_or_b32 s69, s65, 0x4000
	s_or_b32 s70, s66, 0x4000
	s_or_b32 s71, s67, 0x4000
	v_cmp_le_u32_e64 s[76:77], s68, v17
	v_cmp_le_u32_e64 s[78:79], s69, v18
	v_cmp_le_u32_e64 s[80:81], s70, v19
	v_cmp_le_u32_e64 s[82:83], s71, v20
	s_bcnt1_i32_b64 s72, s[76:77]
	s_bcnt1_i32_b64 s73, s[78:79]
	s_bcnt1_i32_b64 s74, s[80:81]
	s_bcnt1_i32_b64 s75, s[82:83]
	s_cmp_ge_u32 s72, 16
	s_cselect_b32 s64, s68, s64
	s_cselect_b32 s94, s72, s94
	s_cmp_ge_u32 s73, 16
	s_cselect_b32 s65, s69, s65
	s_cselect_b32 s95, s73, s95
	s_cmp_ge_u32 s74, 16
	s_cselect_b32 s66, s70, s66
	s_cselect_b32 s96, s74, s96
	s_cmp_ge_u32 s75, 16
	s_cselect_b32 s67, s71, s67
	s_cselect_b32 s97, s75, s97
	s_xor_b32 s84, s94, 16
	s_xor_b32 s85, s95, 16
	s_or_b32 s84, s84, s85
	s_xor_b32 s85, s96, 16
	s_or_b32 s84, s84, s85
	s_xor_b32 s85, s97, 16
	s_or_b32 s84, s84, s85
	s_cmp_eq_u32 s84, 0
	s_cbranch_scc1 .Lrk1_found
	s_or_b32 s68, s64, 0x2000
	s_or_b32 s69, s65, 0x2000
	s_or_b32 s70, s66, 0x2000
	s_or_b32 s71, s67, 0x2000
	v_cmp_le_u32_e64 s[76:77], s68, v17
	v_cmp_le_u32_e64 s[78:79], s69, v18
	v_cmp_le_u32_e64 s[80:81], s70, v19
	v_cmp_le_u32_e64 s[82:83], s71, v20
	s_bcnt1_i32_b64 s72, s[76:77]
	s_bcnt1_i32_b64 s73, s[78:79]
	s_bcnt1_i32_b64 s74, s[80:81]
	s_bcnt1_i32_b64 s75, s[82:83]
	s_cmp_ge_u32 s72, 16
	s_cselect_b32 s64, s68, s64
	s_cselect_b32 s94, s72, s94
	s_cmp_ge_u32 s73, 16
	s_cselect_b32 s65, s69, s65
	s_cselect_b32 s95, s73, s95
	s_cmp_ge_u32 s74, 16
	s_cselect_b32 s66, s70, s66
	s_cselect_b32 s96, s74, s96
	s_cmp_ge_u32 s75, 16
	s_cselect_b32 s67, s71, s67
	s_cselect_b32 s97, s75, s97
	s_or_b32 s68, s64, 0x1000
	s_or_b32 s69, s65, 0x1000
	s_or_b32 s70, s66, 0x1000
	s_or_b32 s71, s67, 0x1000
	v_cmp_le_u32_e64 s[76:77], s68, v17
	v_cmp_le_u32_e64 s[78:79], s69, v18
	v_cmp_le_u32_e64 s[80:81], s70, v19
	v_cmp_le_u32_e64 s[82:83], s71, v20
	s_bcnt1_i32_b64 s72, s[76:77]
	s_bcnt1_i32_b64 s73, s[78:79]
	s_bcnt1_i32_b64 s74, s[80:81]
	s_bcnt1_i32_b64 s75, s[82:83]
	s_cmp_ge_u32 s72, 16
	s_cselect_b32 s64, s68, s64
	s_cselect_b32 s94, s72, s94
	s_cmp_ge_u32 s73, 16
	s_cselect_b32 s65, s69, s65
	s_cselect_b32 s95, s73, s95
	s_cmp_ge_u32 s74, 16
	s_cselect_b32 s66, s70, s66
	s_cselect_b32 s96, s74, s96
	s_cmp_ge_u32 s75, 16
	s_cselect_b32 s67, s71, s67
	s_cselect_b32 s97, s75, s97
	s_xor_b32 s84, s94, 16
	s_xor_b32 s85, s95, 16
	s_or_b32 s84, s84, s85
	s_xor_b32 s85, s96, 16
	s_or_b32 s84, s84, s85
	s_xor_b32 s85, s97, 16
	s_or_b32 s84, s84, s85
	s_cmp_eq_u32 s84, 0
	s_cbranch_scc1 .Lrk1_found
	s_or_b32 s68, s64, 0x800
	s_or_b32 s69, s65, 0x800
	s_or_b32 s70, s66, 0x800
	s_or_b32 s71, s67, 0x800
	v_cmp_le_u32_e64 s[76:77], s68, v17
	v_cmp_le_u32_e64 s[78:79], s69, v18
	v_cmp_le_u32_e64 s[80:81], s70, v19
	v_cmp_le_u32_e64 s[82:83], s71, v20
	s_bcnt1_i32_b64 s72, s[76:77]
	s_bcnt1_i32_b64 s73, s[78:79]
	s_bcnt1_i32_b64 s74, s[80:81]
	s_bcnt1_i32_b64 s75, s[82:83]
	s_cmp_ge_u32 s72, 16
	s_cselect_b32 s64, s68, s64
	s_cselect_b32 s94, s72, s94
	s_cmp_ge_u32 s73, 16
	s_cselect_b32 s65, s69, s65
	s_cselect_b32 s95, s73, s95
	s_cmp_ge_u32 s74, 16
	s_cselect_b32 s66, s70, s66
	s_cselect_b32 s96, s74, s96
	s_cmp_ge_u32 s75, 16
	s_cselect_b32 s67, s71, s67
	s_cselect_b32 s97, s75, s97
	s_or_b32 s68, s64, 0x400
	s_or_b32 s69, s65, 0x400
	s_or_b32 s70, s66, 0x400
	s_or_b32 s71, s67, 0x400
	v_cmp_le_u32_e64 s[76:77], s68, v17
	v_cmp_le_u32_e64 s[78:79], s69, v18
	v_cmp_le_u32_e64 s[80:81], s70, v19
	v_cmp_le_u32_e64 s[82:83], s71, v20
	s_bcnt1_i32_b64 s72, s[76:77]
	s_bcnt1_i32_b64 s73, s[78:79]
	s_bcnt1_i32_b64 s74, s[80:81]
	s_bcnt1_i32_b64 s75, s[82:83]
	s_cmp_ge_u32 s72, 16
	s_cselect_b32 s64, s68, s64
	s_cselect_b32 s94, s72, s94
	s_cmp_ge_u32 s73, 16
	s_cselect_b32 s65, s69, s65
	s_cselect_b32 s95, s73, s95
	s_cmp_ge_u32 s74, 16
	s_cselect_b32 s66, s70, s66
	s_cselect_b32 s96, s74, s96
	s_cmp_ge_u32 s75, 16
	s_cselect_b32 s67, s71, s67
	s_cselect_b32 s97, s75, s97
	s_xor_b32 s84, s94, 16
	s_xor_b32 s85, s95, 16
	s_or_b32 s84, s84, s85
	s_xor_b32 s85, s96, 16
	s_or_b32 s84, s84, s85
	s_xor_b32 s85, s97, 16
	s_or_b32 s84, s84, s85
	s_cmp_eq_u32 s84, 0
	s_cbranch_scc1 .Lrk1_found
	s_or_b32 s68, s64, 0x200
	s_or_b32 s69, s65, 0x200
	s_or_b32 s70, s66, 0x200
	s_or_b32 s71, s67, 0x200
	v_cmp_le_u32_e64 s[76:77], s68, v17
	v_cmp_le_u32_e64 s[78:79], s69, v18
	v_cmp_le_u32_e64 s[80:81], s70, v19
	v_cmp_le_u32_e64 s[82:83], s71, v20
	s_bcnt1_i32_b64 s72, s[76:77]
	s_bcnt1_i32_b64 s73, s[78:79]
	s_bcnt1_i32_b64 s74, s[80:81]
	s_bcnt1_i32_b64 s75, s[82:83]
	s_cmp_ge_u32 s72, 16
	s_cselect_b32 s64, s68, s64
	s_cselect_b32 s94, s72, s94
	s_cmp_ge_u32 s73, 16
	s_cselect_b32 s65, s69, s65
	s_cselect_b32 s95, s73, s95
	s_cmp_ge_u32 s74, 16
	s_cselect_b32 s66, s70, s66
	s_cselect_b32 s96, s74, s96
	s_cmp_ge_u32 s75, 16
	s_cselect_b32 s67, s71, s67
	s_cselect_b32 s97, s75, s97
	s_or_b32 s68, s64, 0x100
	s_or_b32 s69, s65, 0x100
	s_or_b32 s70, s66, 0x100
	s_or_b32 s71, s67, 0x100
	v_cmp_le_u32_e64 s[76:77], s68, v17
	v_cmp_le_u32_e64 s[78:79], s69, v18
	v_cmp_le_u32_e64 s[80:81], s70, v19
	v_cmp_le_u32_e64 s[82:83], s71, v20
	s_bcnt1_i32_b64 s72, s[76:77]
	s_bcnt1_i32_b64 s73, s[78:79]
	s_bcnt1_i32_b64 s74, s[80:81]
	s_bcnt1_i32_b64 s75, s[82:83]
	s_cmp_ge_u32 s72, 16
	s_cselect_b32 s64, s68, s64
	s_cselect_b32 s94, s72, s94
	s_cmp_ge_u32 s73, 16
	s_cselect_b32 s65, s69, s65
	s_cselect_b32 s95, s73, s95
	s_cmp_ge_u32 s74, 16
	s_cselect_b32 s66, s70, s66
	s_cselect_b32 s96, s74, s96
	s_cmp_ge_u32 s75, 16
	s_cselect_b32 s67, s71, s67
	s_cselect_b32 s97, s75, s97
	s_xor_b32 s84, s94, 16
	s_xor_b32 s85, s95, 16
	s_or_b32 s84, s84, s85
	s_xor_b32 s85, s96, 16
	s_or_b32 s84, s84, s85
	s_xor_b32 s85, s97, 16
	s_or_b32 s84, s84, s85
	s_cmp_eq_u32 s84, 0
	s_cbranch_scc1 .Lrk1_found
	s_or_b32 s68, s64, 0x80
	s_or_b32 s69, s65, 0x80
	s_or_b32 s70, s66, 0x80
	s_or_b32 s71, s67, 0x80
	v_cmp_le_u32_e64 s[76:77], s68, v17
	v_cmp_le_u32_e64 s[78:79], s69, v18
	v_cmp_le_u32_e64 s[80:81], s70, v19
	v_cmp_le_u32_e64 s[82:83], s71, v20
	s_bcnt1_i32_b64 s72, s[76:77]
	s_bcnt1_i32_b64 s73, s[78:79]
	s_bcnt1_i32_b64 s74, s[80:81]
	s_bcnt1_i32_b64 s75, s[82:83]
	s_cmp_ge_u32 s72, 16
	s_cselect_b32 s64, s68, s64
	s_cselect_b32 s94, s72, s94
	s_cmp_ge_u32 s73, 16
	s_cselect_b32 s65, s69, s65
	s_cselect_b32 s95, s73, s95
	s_cmp_ge_u32 s74, 16
	s_cselect_b32 s66, s70, s66
	s_cselect_b32 s96, s74, s96
	s_cmp_ge_u32 s75, 16
	s_cselect_b32 s67, s71, s67
	s_cselect_b32 s97, s75, s97
	s_or_b32 s68, s64, 0x40
	s_or_b32 s69, s65, 0x40
	s_or_b32 s70, s66, 0x40
	s_or_b32 s71, s67, 0x40
	v_cmp_le_u32_e64 s[76:77], s68, v17
	v_cmp_le_u32_e64 s[78:79], s69, v18
	v_cmp_le_u32_e64 s[80:81], s70, v19
	v_cmp_le_u32_e64 s[82:83], s71, v20
	s_bcnt1_i32_b64 s72, s[76:77]
	s_bcnt1_i32_b64 s73, s[78:79]
	s_bcnt1_i32_b64 s74, s[80:81]
	s_bcnt1_i32_b64 s75, s[82:83]
	s_cmp_ge_u32 s72, 16
	s_cselect_b32 s64, s68, s64
	s_cselect_b32 s94, s72, s94
	s_cmp_ge_u32 s73, 16
	s_cselect_b32 s65, s69, s65
	s_cselect_b32 s95, s73, s95
	s_cmp_ge_u32 s74, 16
	s_cselect_b32 s66, s70, s66
	s_cselect_b32 s96, s74, s96
	s_cmp_ge_u32 s75, 16
	s_cselect_b32 s67, s71, s67
	s_cselect_b32 s97, s75, s97
	s_xor_b32 s84, s94, 16
	s_xor_b32 s85, s95, 16
	s_or_b32 s84, s84, s85
	s_xor_b32 s85, s96, 16
	s_or_b32 s84, s84, s85
	s_xor_b32 s85, s97, 16
	s_or_b32 s84, s84, s85
	s_cmp_eq_u32 s84, 0
	s_cbranch_scc1 .Lrk1_found
	s_or_b32 s68, s64, 0x20
	s_or_b32 s69, s65, 0x20
	s_or_b32 s70, s66, 0x20
	s_or_b32 s71, s67, 0x20
	v_cmp_le_u32_e64 s[76:77], s68, v17
	v_cmp_le_u32_e64 s[78:79], s69, v18
	v_cmp_le_u32_e64 s[80:81], s70, v19
	v_cmp_le_u32_e64 s[82:83], s71, v20
	s_bcnt1_i32_b64 s72, s[76:77]
	s_bcnt1_i32_b64 s73, s[78:79]
	s_bcnt1_i32_b64 s74, s[80:81]
	s_bcnt1_i32_b64 s75, s[82:83]
	s_cmp_ge_u32 s72, 16
	s_cselect_b32 s64, s68, s64
	s_cselect_b32 s94, s72, s94
	s_cmp_ge_u32 s73, 16
	s_cselect_b32 s65, s69, s65
	s_cselect_b32 s95, s73, s95
	s_cmp_ge_u32 s74, 16
	s_cselect_b32 s66, s70, s66
	s_cselect_b32 s96, s74, s96
	s_cmp_ge_u32 s75, 16
	s_cselect_b32 s67, s71, s67
	s_cselect_b32 s97, s75, s97
	s_or_b32 s68, s64, 0x10
	s_or_b32 s69, s65, 0x10
	s_or_b32 s70, s66, 0x10
	s_or_b32 s71, s67, 0x10
	v_cmp_le_u32_e64 s[76:77], s68, v17
	v_cmp_le_u32_e64 s[78:79], s69, v18
	v_cmp_le_u32_e64 s[80:81], s70, v19
	v_cmp_le_u32_e64 s[82:83], s71, v20
	s_bcnt1_i32_b64 s72, s[76:77]
	s_bcnt1_i32_b64 s73, s[78:79]
	s_bcnt1_i32_b64 s74, s[80:81]
	s_bcnt1_i32_b64 s75, s[82:83]
	s_cmp_ge_u32 s72, 16
	s_cselect_b32 s64, s68, s64
	s_cselect_b32 s94, s72, s94
	s_cmp_ge_u32 s73, 16
	s_cselect_b32 s65, s69, s65
	s_cselect_b32 s95, s73, s95
	s_cmp_ge_u32 s74, 16
	s_cselect_b32 s66, s70, s66
	s_cselect_b32 s96, s74, s96
	s_cmp_ge_u32 s75, 16
	s_cselect_b32 s67, s71, s67
	s_cselect_b32 s97, s75, s97
	s_xor_b32 s84, s94, 16
	s_xor_b32 s85, s95, 16
	s_or_b32 s84, s84, s85
	s_xor_b32 s85, s96, 16
	s_or_b32 s84, s84, s85
	s_xor_b32 s85, s97, 16
	s_or_b32 s84, s84, s85
	s_cmp_eq_u32 s84, 0
	s_cbranch_scc1 .Lrk1_found
	s_or_b32 s68, s64, 0x8
	s_or_b32 s69, s65, 0x8
	s_or_b32 s70, s66, 0x8
	s_or_b32 s71, s67, 0x8
	v_cmp_le_u32_e64 s[76:77], s68, v17
	v_cmp_le_u32_e64 s[78:79], s69, v18
	v_cmp_le_u32_e64 s[80:81], s70, v19
	v_cmp_le_u32_e64 s[82:83], s71, v20
	s_bcnt1_i32_b64 s72, s[76:77]
	s_bcnt1_i32_b64 s73, s[78:79]
	s_bcnt1_i32_b64 s74, s[80:81]
	s_bcnt1_i32_b64 s75, s[82:83]
	s_cmp_ge_u32 s72, 16
	s_cselect_b32 s64, s68, s64
	s_cselect_b32 s94, s72, s94
	s_cmp_ge_u32 s73, 16
	s_cselect_b32 s65, s69, s65
	s_cselect_b32 s95, s73, s95
	s_cmp_ge_u32 s74, 16
	s_cselect_b32 s66, s70, s66
	s_cselect_b32 s96, s74, s96
	s_cmp_ge_u32 s75, 16
	s_cselect_b32 s67, s71, s67
	s_cselect_b32 s97, s75, s97
	s_or_b32 s68, s64, 0x4
	s_or_b32 s69, s65, 0x4
	s_or_b32 s70, s66, 0x4
	s_or_b32 s71, s67, 0x4
	v_cmp_le_u32_e64 s[76:77], s68, v17
	v_cmp_le_u32_e64 s[78:79], s69, v18
	v_cmp_le_u32_e64 s[80:81], s70, v19
	v_cmp_le_u32_e64 s[82:83], s71, v20
	s_bcnt1_i32_b64 s72, s[76:77]
	s_bcnt1_i32_b64 s73, s[78:79]
	s_bcnt1_i32_b64 s74, s[80:81]
	s_bcnt1_i32_b64 s75, s[82:83]
	s_cmp_ge_u32 s72, 16
	s_cselect_b32 s64, s68, s64
	s_cselect_b32 s94, s72, s94
	s_cmp_ge_u32 s73, 16
	s_cselect_b32 s65, s69, s65
	s_cselect_b32 s95, s73, s95
	s_cmp_ge_u32 s74, 16
	s_cselect_b32 s66, s70, s66
	s_cselect_b32 s96, s74, s96
	s_cmp_ge_u32 s75, 16
	s_cselect_b32 s67, s71, s67
	s_cselect_b32 s97, s75, s97
	s_xor_b32 s84, s94, 16
	s_xor_b32 s85, s95, 16
	s_or_b32 s84, s84, s85
	s_xor_b32 s85, s96, 16
	s_or_b32 s84, s84, s85
	s_xor_b32 s85, s97, 16
	s_or_b32 s84, s84, s85
	s_cmp_eq_u32 s84, 0
	s_cbranch_scc1 .Lrk1_found
	s_or_b32 s68, s64, 0x2
	s_or_b32 s69, s65, 0x2
	s_or_b32 s70, s66, 0x2
	s_or_b32 s71, s67, 0x2
	v_cmp_le_u32_e64 s[76:77], s68, v17
	v_cmp_le_u32_e64 s[78:79], s69, v18
	v_cmp_le_u32_e64 s[80:81], s70, v19
	v_cmp_le_u32_e64 s[82:83], s71, v20
	s_bcnt1_i32_b64 s72, s[76:77]
	s_bcnt1_i32_b64 s73, s[78:79]
	s_bcnt1_i32_b64 s74, s[80:81]
	s_bcnt1_i32_b64 s75, s[82:83]
	s_cmp_ge_u32 s72, 16
	s_cselect_b32 s64, s68, s64
	s_cselect_b32 s94, s72, s94
	s_cmp_ge_u32 s73, 16
	s_cselect_b32 s65, s69, s65
	s_cselect_b32 s95, s73, s95
	s_cmp_ge_u32 s74, 16
	s_cselect_b32 s66, s70, s66
	s_cselect_b32 s96, s74, s96
	s_cmp_ge_u32 s75, 16
	s_cselect_b32 s67, s71, s67
	s_cselect_b32 s97, s75, s97
	s_or_b32 s68, s64, 0x1
	s_or_b32 s69, s65, 0x1
	s_or_b32 s70, s66, 0x1
	s_or_b32 s71, s67, 0x1
	v_cmp_le_u32_e64 s[76:77], s68, v17
	v_cmp_le_u32_e64 s[78:79], s69, v18
	v_cmp_le_u32_e64 s[80:81], s70, v19
	v_cmp_le_u32_e64 s[82:83], s71, v20
	s_bcnt1_i32_b64 s72, s[76:77]
	s_bcnt1_i32_b64 s73, s[78:79]
	s_bcnt1_i32_b64 s74, s[80:81]
	s_bcnt1_i32_b64 s75, s[82:83]
	s_cmp_ge_u32 s72, 16
	s_cselect_b32 s64, s68, s64
	s_cselect_b32 s94, s72, s94
	s_cmp_ge_u32 s73, 16
	s_cselect_b32 s65, s69, s65
	s_cselect_b32 s95, s73, s95
	s_cmp_ge_u32 s74, 16
	s_cselect_b32 s66, s70, s66
	s_cselect_b32 s96, s74, s96
	s_cmp_ge_u32 s75, 16
	s_cselect_b32 s67, s71, s67
	s_cselect_b32 s97, s75, s97
